# M-stage rewrite + hand-written packed-f32 SSD conv with scale-table reads hoisted + static s_setprio 1 for the four full conv waves
# speedup vs baseline: 1.0094x; 1.0016x over previous
; __device__ __forceinline__ float bflo(unsigned u) { return __uint_as_float(u << 16); }
; __device__ __forceinline__ float bfhi(unsigned u) { return __uint_as_float(u & 0xffff0000u); }
; __device__ __forceinline__ unsigned short f2bf(float f) { return (unsigned short)(cvt_pk_bf16(f, 0.f) & 0xffffu); }
; __device__ __forceinline__ float siluf_(float v) { return v * __builtin_amdgcn_rcpf(1.0f + __expf(-v)); }
; #define SSD_ISSUE_DT(c_) do { const int c__ = (c_); const float* dp = dtraw + (rowbase + (size_t)c__ * 128 + lane) * 32 + head; dtn0 = dp[0]; dtn1 = dp[64 * 32]; } while (0)
; __device__ __forceinline__ void ssd_item(const Params& p, LAS unsigned char* lds, int bl, int head, int dry) {
;     ...
;         __syncthreads();
; #pragma unroll
;         for (int r = 0; r < 16; ++r) { const int row = (r & 3) + 8 * (r >> 2) + rsub; SB[(pt * 32 + row) * SLD + nt * 32 + cl] = f2bf(accS[r]); }
;         { const bf16_t* zp = proj + (r0 + ti_d * 32 + cl) * PLD + COL_Z + head * 64 + pc_d * 32 + rsub;
; #pragma unroll
;           for (int g4 = 0; g4 < 4; ++g4) zr[g4] = *(const u32x2*)(zp + 8 * g4); }
;         SSD_ISSUE_DT(c + 1 < 32 ? c + 1 : 31);
;         __builtin_amdgcn_sched_barrier(0);
;         if (cact) {
;             if (c == 0 && rg == 0) { raw[0] = (u32x2){0u, 0u}; raw[1] = (u32x2){0u, 0u}; raw[2] = (u32x2){0u, 0u}; }
; #pragma unroll
;             for (int seg = 0; seg < 4; ++seg) {
;                 float val[8][4];
; #pragma unroll
;                 for (int j = 0; j < 8; ++j) { const int i = seg * 8 + j;
;                     const u32x2 x0 = raw[i], x1 = raw[i + 1], x2 = raw[i + 2], x3 = raw[i + 3];
;                     float v0 = cbv[0] + cw0[0] * bflo(x0.x) + cw1[0] * bflo(x1.x) + cw2[0] * bflo(x2.x) + cw3[0] * bflo(x3.x);
;                     float v1 = cbv[1] + cw0[1] * bfhi(x0.x) + cw1[1] * bfhi(x1.x) + cw2[1] * bfhi(x2.x) + cw3[1] * bfhi(x3.x);
;                     float v2 = cbv[2] + cw0[2] * bflo(x0.y) + cw1[2] * bflo(x1.y) + cw2[2] * bflo(x2.y) + cw3[2] * bflo(x3.y);
;                     float v3 = cbv[3] + cw0[3] * bfhi(x0.y) + cw1[3] * bfhi(x1.y) + cw2[3] * bfhi(x2.y) + cw3[3] * bfhi(x3.y);
;                     val[j][0] = siluf_(v0); val[j][1] = siluf_(v1); val[j][2] = siluf_(v2); val[j][3] = siluf_(v3); }
.LBB0_224:
	s_waitcnt lgkmcnt(0)
	s_barrier
	v_cvt_pk_bf16_f32 v16, v0, v185
	ds_write_b16 v186, v16
	v_cvt_pk_bf16_f32 v16, v1, v185
	ds_write_b16 v186, v16 offset:272
	v_cvt_pk_bf16_f32 v16, v2, v185
	ds_write_b16 v186, v16 offset:544
	v_cvt_pk_bf16_f32 v16, v3, v185
	ds_write_b16 v186, v16 offset:816
	v_cvt_pk_bf16_f32 v16, v4, v185
	ds_write_b16 v186, v16 offset:2176
	v_cvt_pk_bf16_f32 v16, v5, v185
	ds_write_b16 v186, v16 offset:2448
	v_cvt_pk_bf16_f32 v16, v6, v185
	ds_write_b16 v186, v16 offset:2720
	v_cvt_pk_bf16_f32 v16, v7, v185
	ds_write_b16 v186, v16 offset:2992
	v_cvt_pk_bf16_f32 v16, v8, v185
	ds_write_b16 v186, v16 offset:4352
	v_cvt_pk_bf16_f32 v16, v9, v185
	ds_write_b16 v186, v16 offset:4624
	v_cvt_pk_bf16_f32 v16, v10, v185
	ds_write_b16 v186, v16 offset:4896
	v_cvt_pk_bf16_f32 v16, v11, v185
	ds_write_b16 v186, v16 offset:5168
	v_cvt_pk_bf16_f32 v16, v12, v185
	s_lshl_b32 s0, s58, 7
	ds_write_b16 v186, v16 offset:6528
	v_cvt_pk_bf16_f32 v16, v13, v185
	s_bitcmp1_b32 s58, 0
	ds_write_b16 v186, v16 offset:6800
	v_cvt_pk_bf16_f32 v16, v14, v185
	s_cselect_b32 s1, 0x600, 0
	ds_write_b16 v186, v16 offset:7072
	v_cvt_pk_bf16_f32 v16, v15, v185
	s_or_b32 s36, s54, s0
	s_mov_b32 s37, s55
	ds_write_b16 v186, v16 offset:7344
	v_lshl_add_u64 v[16:17], v[72:73], 0, s[36:37]
	s_add_i32 s63, s1, 0
	v_mad_u64_u32 v[18:19], s[0:1], v16, s33, v[74:75]
	s_add_i32 s62, s58, 1
	s_add_i32 s63, s63, 0x22000
	v_mov_b32_e32 v16, v19
	s_lshl_b32 s2, s62, 7
	v_mad_u64_u32 v[16:17], s[0:1], v17, s33, v[16:17]
	s_cmp_eq_u32 s58, 31
	s_cselect_b64 s[0:1], -1, 0
	s_and_b64 s[56:57], s[0:1], exec
	s_cselect_b32 s2, 0xf80, s2
	v_mov_b32_e32 v19, v16
	v_lshl_add_u64 v[16:17], v[70:71], 0, s[2:3]
	v_lshlrev_b64 v[16:17], 7, v[16:17]
	v_lshl_add_u64 v[16:17], s[52:53], 0, v[16:17]
	global_load_dwordx2 v[104:105], v[18:19], off
	global_load_dwordx2 v[98:99], v[18:19], off offset:16
	global_load_dwordx2 v[96:97], v[18:19], off offset:32
	global_load_dwordx2 v[90:91], v[18:19], off offset:48
	global_load_dword v157, v[16:17], off
	v_add_co_u32_e32 v16, vcc, 0x2000, v16
	s_nop 1
	v_addc_co_u32_e32 v17, vcc, 0, v17, vcc
	global_load_dword v156, v[16:17], off
	v_mov_b32_e32 v16, 0
	s_and_saveexec_b64 s[56:57], s[40:41]
	s_cbranch_execz .LBB0_242
	s_cmp_lt_u32 s98, 4
	s_cbranch_scc1 .Lcw_prio
	s_waitcnt vmcnt(6)
	s_branch .Lcw_skip
.Lcw_prio:
	s_setprio 1
.Lcw_skip:
	v_mov_b32_e32 v214, 0xbfb8aa3b
	v_mov_b32_e32 v215, 0xbfb8aa3b
	v_mov_b32_e32 v216, 1.0
	v_mov_b32_e32 v217, 1.0
	v_add_u32_e32 v218, s63, v182
	v_lshl_add_u32 v218, v170, 2, v218
	v_or_b32_e32 v194, s58, v166
	v_cmp_eq_u32_e32 vcc, 0, v194
	s_waitcnt vmcnt(37)
	s_nop 0
	v_cndmask_b32_e64 v150, v150, 0, vcc
	v_cndmask_b32_e64 v151, v151, 0, vcc
	v_cndmask_b32_e64 v152, v152, 0, vcc
	v_cndmask_b32_e64 v153, v153, 0, vcc
	v_cndmask_b32_e64 v154, v154, 0, vcc
	v_cndmask_b32_e64 v155, v155, 0, vcc
	ds_read_b128 v[206:209], v218
	ds_read_b128 v[210:213], v218 offset:16
	v_lshlrev_b32_e32 v194, 16, v150
	v_and_b32_e32 v195, 0xffff0000, v150
	v_lshlrev_b32_e32 v196, 16, v151
	v_and_b32_e32 v197, 0xffff0000, v151
	v_pk_fma_f32 v[16:17], v[48:49], v[194:195], v[64:65]
	v_pk_fma_f32 v[18:19], v[50:51], v[196:197], v[66:67]
	v_lshlrev_b32_e32 v198, 16, v152
	v_and_b32_e32 v199, 0xffff0000, v152
	v_lshlrev_b32_e32 v200, 16, v153
	v_and_b32_e32 v201, 0xffff0000, v153
	v_pk_fma_f32 v[20:21], v[48:49], v[198:199], v[64:65]
	v_pk_fma_f32 v[22:23], v[50:51], v[200:201], v[66:67]
	v_pk_fma_f32 v[16:17], v[52:53], v[198:199], v[16:17]
	v_pk_fma_f32 v[18:19], v[54:55], v[200:201], v[18:19]
	v_lshlrev_b32_e32 v194, 16, v154
	v_and_b32_e32 v195, 0xffff0000, v154
	v_lshlrev_b32_e32 v196, 16, v155
	v_and_b32_e32 v197, 0xffff0000, v155
	v_pk_fma_f32 v[24:25], v[48:49], v[194:195], v[64:65]
	v_pk_fma_f32 v[26:27], v[50:51], v[196:197], v[66:67]
	v_pk_fma_f32 v[20:21], v[52:53], v[194:195], v[20:21]
	v_pk_fma_f32 v[22:23], v[54:55], v[196:197], v[22:23]
	v_pk_fma_f32 v[16:17], v[56:57], v[194:195], v[16:17]
	v_pk_fma_f32 v[18:19], v[58:59], v[196:197], v[18:19]
	v_lshlrev_b32_e32 v198, 16, v148
	v_and_b32_e32 v199, 0xffff0000, v148
	v_lshlrev_b32_e32 v200, 16, v149
	v_and_b32_e32 v201, 0xffff0000, v149
	v_pk_fma_f32 v[28:29], v[48:49], v[198:199], v[64:65]
	v_pk_fma_f32 v[30:31], v[50:51], v[200:201], v[66:67]
	v_pk_fma_f32 v[24:25], v[52:53], v[198:199], v[24:25]
	v_pk_fma_f32 v[26:27], v[54:55], v[200:201], v[26:27]
	v_pk_fma_f32 v[20:21], v[56:57], v[198:199], v[20:21]
	v_pk_fma_f32 v[22:23], v[58:59], v[200:201], v[22:23]
	v_pk_fma_f32 v[16:17], v[60:61], v[198:199], v[16:17]
	v_pk_fma_f32 v[18:19], v[62:63], v[200:201], v[18:19]
	s_waitcnt vmcnt(36)
	v_lshlrev_b32_e32 v194, 16, v146
	v_and_b32_e32 v195, 0xffff0000, v146
	v_lshlrev_b32_e32 v196, 16, v147
	v_and_b32_e32 v197, 0xffff0000, v147
	v_pk_fma_f32 v[32:33], v[48:49], v[194:195], v[64:65]
	v_pk_fma_f32 v[34:35], v[50:51], v[196:197], v[66:67]
	v_pk_fma_f32 v[28:29], v[52:53], v[194:195], v[28:29]
	v_pk_fma_f32 v[30:31], v[54:55], v[196:197], v[30:31]
	v_pk_fma_f32 v[24:25], v[56:57], v[194:195], v[24:25]
	v_pk_fma_f32 v[26:27], v[58:59], v[196:197], v[26:27]
	v_pk_fma_f32 v[20:21], v[60:61], v[194:195], v[20:21]
	v_pk_fma_f32 v[22:23], v[62:63], v[196:197], v[22:23]
	s_waitcnt vmcnt(35)
	v_lshlrev_b32_e32 v198, 16, v144
	v_and_b32_e32 v199, 0xffff0000, v144
	v_lshlrev_b32_e32 v200, 16, v145
	v_and_b32_e32 v201, 0xffff0000, v145
	v_pk_fma_f32 v[36:37], v[48:49], v[198:199], v[64:65]
	v_pk_fma_f32 v[38:39], v[50:51], v[200:201], v[66:67]
	v_pk_fma_f32 v[32:33], v[52:53], v[198:199], v[32:33]
	v_pk_fma_f32 v[34:35], v[54:55], v[200:201], v[34:35]
	v_pk_fma_f32 v[28:29], v[56:57], v[198:199], v[28:29]
	v_pk_fma_f32 v[30:31], v[58:59], v[200:201], v[30:31]
	v_pk_fma_f32 v[24:25], v[60:61], v[198:199], v[24:25]
	v_pk_fma_f32 v[26:27], v[62:63], v[200:201], v[26:27]
	s_waitcnt vmcnt(34)
; #define LAS __attribute__((address_space(3)))
; __device__ __forceinline__ float bflo(unsigned u) { return __uint_as_float(u << 16); }
; __device__ __forceinline__ float bfhi(unsigned u) { return __uint_as_float(u & 0xffff0000u); }
; __device__ __forceinline__ float siluf_(float v) { return v * __builtin_amdgcn_rcpf(1.0f + __expf(-v)); }
; __device__ __forceinline__ void ssd_item(const Params& p, LAS unsigned char* lds, int bl, int head, int dry) {
;     ...
;                 for (int j = 0; j < 8; ++j) { const int i = seg * 8 + j;
;                     const u32x2 x0 = raw[i], x1 = raw[i + 1], x2 = raw[i + 2], x3 = raw[i + 3];
;                     float v0 = cbv[0] + cw0[0] * bflo(x0.x) + cw1[0] * bflo(x1.x) + cw2[0] * bflo(x2.x) + cw3[0] * bflo(x3.x);
;                     float v1 = cbv[1] + cw0[1] * bfhi(x0.x) + cw1[1] * bfhi(x1.x) + cw2[1] * bfhi(x2.x) + cw3[1] * bfhi(x3.x);
;                     float v2 = cbv[2] + cw0[2] * bflo(x0.y) + cw1[2] * bflo(x1.y) + cw2[2] * bflo(x2.y) + cw3[2] * bflo(x3.y);
;                     float v3 = cbv[3] + cw0[3] * bfhi(x0.y) + cw1[3] * bfhi(x1.y) + cw2[3] * bfhi(x2.y) + cw3[3] * bfhi(x3.y);
;                     val[j][0] = siluf_(v0); val[j][1] = siluf_(v1); val[j][2] = siluf_(v2); val[j][3] = siluf_(v3); }
;                 const int lb = rg * 32 + seg * 8;
;                 if (kind != 0) { LAS bf16_t* rm = (kind == 1 ? BMm : CM) + lb * SLD + n4;
	v_lshlrev_b32_e32 v194, 16, v142
	v_and_b32_e32 v195, 0xffff0000, v142
	v_lshlrev_b32_e32 v196, 16, v143
	v_and_b32_e32 v197, 0xffff0000, v143
	v_pk_fma_f32 v[40:41], v[48:49], v[194:195], v[64:65]
	v_pk_fma_f32 v[42:43], v[50:51], v[196:197], v[66:67]
	v_pk_fma_f32 v[36:37], v[52:53], v[194:195], v[36:37]
	v_pk_fma_f32 v[38:39], v[54:55], v[196:197], v[38:39]
	v_pk_fma_f32 v[32:33], v[56:57], v[194:195], v[32:33]
	v_pk_fma_f32 v[34:35], v[58:59], v[196:197], v[34:35]
	v_pk_fma_f32 v[28:29], v[60:61], v[194:195], v[28:29]
	v_pk_fma_f32 v[30:31], v[62:63], v[196:197], v[30:31]
	s_waitcnt vmcnt(33)
	v_lshlrev_b32_e32 v198, 16, v140
	v_and_b32_e32 v199, 0xffff0000, v140
	v_lshlrev_b32_e32 v200, 16, v141
	v_and_b32_e32 v201, 0xffff0000, v141
	v_pk_fma_f32 v[44:45], v[48:49], v[198:199], v[64:65]
	v_pk_fma_f32 v[46:47], v[50:51], v[200:201], v[66:67]
	v_pk_fma_f32 v[40:41], v[52:53], v[198:199], v[40:41]
	v_pk_fma_f32 v[42:43], v[54:55], v[200:201], v[42:43]
	v_pk_fma_f32 v[36:37], v[56:57], v[198:199], v[36:37]
	v_pk_fma_f32 v[38:39], v[58:59], v[200:201], v[38:39]
	v_pk_fma_f32 v[32:33], v[60:61], v[198:199], v[32:33]
	v_pk_fma_f32 v[34:35], v[62:63], v[200:201], v[34:35]
	s_waitcnt vmcnt(32)
	v_lshlrev_b32_e32 v194, 16, v138
	v_and_b32_e32 v195, 0xffff0000, v138
	v_lshlrev_b32_e32 v196, 16, v139
	v_and_b32_e32 v197, 0xffff0000, v139
	v_pk_fma_f32 v[44:45], v[52:53], v[194:195], v[44:45]
	v_pk_fma_f32 v[46:47], v[54:55], v[196:197], v[46:47]
	v_pk_fma_f32 v[40:41], v[56:57], v[194:195], v[40:41]
	v_pk_fma_f32 v[42:43], v[58:59], v[196:197], v[42:43]
	v_pk_fma_f32 v[36:37], v[60:61], v[194:195], v[36:37]
	v_pk_fma_f32 v[38:39], v[62:63], v[196:197], v[38:39]
	s_waitcnt vmcnt(31)
	v_lshlrev_b32_e32 v198, 16, v136
	v_and_b32_e32 v199, 0xffff0000, v136
	v_lshlrev_b32_e32 v200, 16, v137
	v_and_b32_e32 v201, 0xffff0000, v137
	v_pk_fma_f32 v[44:45], v[56:57], v[198:199], v[44:45]
	v_pk_fma_f32 v[46:47], v[58:59], v[200:201], v[46:47]
	v_pk_fma_f32 v[40:41], v[60:61], v[198:199], v[40:41]
	v_pk_fma_f32 v[42:43], v[62:63], v[200:201], v[42:43]
	s_waitcnt vmcnt(30)
	v_lshlrev_b32_e32 v194, 16, v134
	v_and_b32_e32 v195, 0xffff0000, v134
	v_lshlrev_b32_e32 v196, 16, v135
	v_and_b32_e32 v197, 0xffff0000, v135
	v_pk_fma_f32 v[44:45], v[60:61], v[194:195], v[44:45]
	v_pk_fma_f32 v[46:47], v[62:63], v[196:197], v[46:47]
	v_pk_mul_f32 v[202:203], v[16:17], v[214:215]
	v_pk_mul_f32 v[204:205], v[18:19], v[214:215]
	v_exp_f32_e32 v202, v202
	v_exp_f32_e32 v203, v203
	v_exp_f32_e32 v204, v204
	v_exp_f32_e32 v205, v205
	v_pk_add_f32 v[202:203], v[202:203], v[216:217]
	v_pk_add_f32 v[204:205], v[204:205], v[216:217]
	v_rcp_f32_e32 v202, v202
	v_rcp_f32_e32 v203, v203
	v_rcp_f32_e32 v204, v204
	v_rcp_f32_e32 v205, v205
	v_pk_mul_f32 v[16:17], v[16:17], v[202:203]
	v_pk_mul_f32 v[18:19], v[18:19], v[204:205]
	v_pk_mul_f32 v[202:203], v[20:21], v[214:215]
	v_pk_mul_f32 v[204:205], v[22:23], v[214:215]
	v_exp_f32_e32 v202, v202
	v_exp_f32_e32 v203, v203
	v_exp_f32_e32 v204, v204
	v_exp_f32_e32 v205, v205
	v_pk_add_f32 v[202:203], v[202:203], v[216:217]
	v_pk_add_f32 v[204:205], v[204:205], v[216:217]
	v_rcp_f32_e32 v202, v202
	v_rcp_f32_e32 v203, v203
	v_rcp_f32_e32 v204, v204
	v_rcp_f32_e32 v205, v205
	v_pk_mul_f32 v[20:21], v[20:21], v[202:203]
	v_pk_mul_f32 v[22:23], v[22:23], v[204:205]
	v_pk_mul_f32 v[202:203], v[24:25], v[214:215]
	v_pk_mul_f32 v[204:205], v[26:27], v[214:215]
	v_exp_f32_e32 v202, v202
	v_exp_f32_e32 v203, v203
	v_exp_f32_e32 v204, v204
	v_exp_f32_e32 v205, v205
	v_pk_add_f32 v[202:203], v[202:203], v[216:217]
	v_pk_add_f32 v[204:205], v[204:205], v[216:217]
	v_rcp_f32_e32 v202, v202
	v_rcp_f32_e32 v203, v203
	v_rcp_f32_e32 v204, v204
	v_rcp_f32_e32 v205, v205
	v_pk_mul_f32 v[24:25], v[24:25], v[202:203]
	v_pk_mul_f32 v[26:27], v[26:27], v[204:205]
	v_pk_mul_f32 v[202:203], v[28:29], v[214:215]
	v_pk_mul_f32 v[204:205], v[30:31], v[214:215]
	v_exp_f32_e32 v202, v202
	v_exp_f32_e32 v203, v203
	v_exp_f32_e32 v204, v204
	v_exp_f32_e32 v205, v205
	v_pk_add_f32 v[202:203], v[202:203], v[216:217]
	v_pk_add_f32 v[204:205], v[204:205], v[216:217]
	v_rcp_f32_e32 v202, v202
	v_rcp_f32_e32 v203, v203
	v_rcp_f32_e32 v204, v204
	v_rcp_f32_e32 v205, v205
	v_pk_mul_f32 v[28:29], v[28:29], v[202:203]
	v_pk_mul_f32 v[30:31], v[30:31], v[204:205]
	v_pk_mul_f32 v[202:203], v[32:33], v[214:215]
	v_pk_mul_f32 v[204:205], v[34:35], v[214:215]
	v_exp_f32_e32 v202, v202
	v_exp_f32_e32 v203, v203
	v_exp_f32_e32 v204, v204
	v_exp_f32_e32 v205, v205
	v_pk_add_f32 v[202:203], v[202:203], v[216:217]
	v_pk_add_f32 v[204:205], v[204:205], v[216:217]
	v_rcp_f32_e32 v202, v202
	v_rcp_f32_e32 v203, v203
	v_rcp_f32_e32 v204, v204
	v_rcp_f32_e32 v205, v205
	v_pk_mul_f32 v[32:33], v[32:33], v[202:203]
	v_pk_mul_f32 v[34:35], v[34:35], v[204:205]
	v_pk_mul_f32 v[202:203], v[36:37], v[214:215]
	v_pk_mul_f32 v[204:205], v[38:39], v[214:215]
	v_exp_f32_e32 v202, v202
	v_exp_f32_e32 v203, v203
	v_exp_f32_e32 v204, v204
	v_exp_f32_e32 v205, v205
	v_pk_add_f32 v[202:203], v[202:203], v[216:217]
	v_pk_add_f32 v[204:205], v[204:205], v[216:217]
	v_rcp_f32_e32 v202, v202
	v_rcp_f32_e32 v203, v203
	v_rcp_f32_e32 v204, v204
	v_rcp_f32_e32 v205, v205
	v_pk_mul_f32 v[36:37], v[36:37], v[202:203]
	v_pk_mul_f32 v[38:39], v[38:39], v[204:205]
	v_pk_mul_f32 v[202:203], v[40:41], v[214:215]
	v_pk_mul_f32 v[204:205], v[42:43], v[214:215]
	v_exp_f32_e32 v202, v202
	v_exp_f32_e32 v203, v203
	v_exp_f32_e32 v204, v204
	v_exp_f32_e32 v205, v205
	v_pk_add_f32 v[202:203], v[202:203], v[216:217]
	v_pk_add_f32 v[204:205], v[204:205], v[216:217]
	v_rcp_f32_e32 v202, v202
	v_rcp_f32_e32 v203, v203
	v_rcp_f32_e32 v204, v204
	v_rcp_f32_e32 v205, v205
	v_pk_mul_f32 v[40:41], v[40:41], v[202:203]
	v_pk_mul_f32 v[42:43], v[42:43], v[204:205]
	v_pk_mul_f32 v[202:203], v[44:45], v[214:215]
	v_pk_mul_f32 v[204:205], v[46:47], v[214:215]
	v_exp_f32_e32 v202, v202
	v_exp_f32_e32 v203, v203
	v_exp_f32_e32 v204, v204
	v_exp_f32_e32 v205, v205
	v_pk_add_f32 v[202:203], v[202:203], v[216:217]
	v_pk_add_f32 v[204:205], v[204:205], v[216:217]
	v_rcp_f32_e32 v202, v202
	v_rcp_f32_e32 v203, v203
	v_rcp_f32_e32 v204, v204
	v_rcp_f32_e32 v205, v205
	v_pk_mul_f32 v[44:45], v[44:45], v[202:203]
	v_pk_mul_f32 v[46:47], v[46:47], v[204:205]
	s_waitcnt lgkmcnt(0)
	s_and_saveexec_b64 vcc, s[38:39]
	s_cbranch_execz .Lcv_rm_0
; __device__ __forceinline__ unsigned cvt_pk_bf16(float lo, float hi) { unsigned r; asm volatile("v_cvt_pk_bf16_f32 %0, %1, %2" : "=v"(r) : "v"(lo), "v"(hi)); return r; }
; #define LAS __attribute__((address_space(3)))
; __device__ __forceinline__ float bflo(unsigned u) { return __uint_as_float(u << 16); }
; __device__ __forceinline__ float bfhi(unsigned u) { return __uint_as_float(u & 0xffff0000u); }
; __device__ __forceinline__ void ssd_item(const Params& p, LAS unsigned char* lds, int bl, int head, int dry) {
;     ...
;                 for (int j = 0; j < 8; ++j) { const int i = seg * 8 + j;
;                     const u32x2 x0 = raw[i], x1 = raw[i + 1], x2 = raw[i + 2], x3 = raw[i + 3];
;                     float v0 = cbv[0] + cw0[0] * bflo(x0.x) + cw1[0] * bflo(x1.x) + cw2[0] * bflo(x2.x) + cw3[0] * bflo(x3.x);
;                     float v1 = cbv[1] + cw0[1] * bfhi(x0.x) + cw1[1] * bfhi(x1.x) + cw2[1] * bfhi(x2.x) + cw3[1] * bfhi(x3.x);
;                     float v2 = cbv[2] + cw0[2] * bflo(x0.y) + cw1[2] * bflo(x1.y) + cw2[2] * bflo(x2.y) + cw3[2] * bflo(x3.y);
;                     float v3 = cbv[3] + cw0[3] * bfhi(x0.y) + cw1[3] * bfhi(x1.y) + cw2[3] * bfhi(x2.y) + cw3[3] * bfhi(x3.y);
;                     val[j][0] = siluf_(v0); val[j][1] = siluf_(v1); val[j][2] = siluf_(v2); val[j][3] = siluf_(v3); }
;                 const int lb = rg * 32 + seg * 8;
;                 if (kind != 0) { LAS bf16_t* rm = (kind == 1 ? BMm : CM) + lb * SLD + n4;
; #pragma unroll
;                     for (int j = 0; j < 8; ++j) { u32x2 o; o.x = cvt_pk_bf16(val[j][0], val[j][1]); o.y = cvt_pk_bf16(val[j][2], val[j][3]); *(LAS u32x2*)(rm + j * SLD) = o; } }
;                 if (kind != 2) { LAS float* sc = (kind == 0 ? fdt : fwl) + lb; LAS bf16_t* tp = (kind == 0 ? XT : BT) + n4 * SLD + lb;
;                     float scl[8];
; #pragma unroll
;                     for (int j = 0; j < 8; ++j) scl[j] = sc[j];
; #pragma unroll
;                     for (int e = 0; e < 4; ++e) { u32x4 o; o.x = cvt_pk_bf16(val[0][e] * scl[0], val[1][e] * scl[1]); o.y = cvt_pk_bf16(val[2][e] * scl[2], val[3][e] * scl[3]);
;                         o.z = cvt_pk_bf16(val[4][e] * scl[4], val[5][e] * scl[5]); o.w = cvt_pk_bf16(val[6][e] * scl[6], val[7][e] * scl[7]); *(LAS u32x4*)(tp + e * SLD) = o; } }
	v_cvt_pk_bf16_f32 v194, v16, v17
	v_cvt_pk_bf16_f32 v195, v18, v19
	ds_write_b64 v187, v[194:195]
	v_cvt_pk_bf16_f32 v196, v20, v21
	v_cvt_pk_bf16_f32 v197, v22, v23
	ds_write_b64 v187, v[196:197] offset:272
	v_cvt_pk_bf16_f32 v194, v24, v25
	v_cvt_pk_bf16_f32 v195, v26, v27
	ds_write_b64 v187, v[194:195] offset:544
	v_cvt_pk_bf16_f32 v196, v28, v29
	v_cvt_pk_bf16_f32 v197, v30, v31
	ds_write_b64 v187, v[196:197] offset:816
	v_cvt_pk_bf16_f32 v194, v32, v33
	v_cvt_pk_bf16_f32 v195, v34, v35
	ds_write_b64 v187, v[194:195] offset:1088
	v_cvt_pk_bf16_f32 v196, v36, v37
	v_cvt_pk_bf16_f32 v197, v38, v39
	ds_write_b64 v187, v[196:197] offset:1360
	v_cvt_pk_bf16_f32 v194, v40, v41
	v_cvt_pk_bf16_f32 v195, v42, v43
	ds_write_b64 v187, v[194:195] offset:1632
	v_cvt_pk_bf16_f32 v196, v44, v45
	v_cvt_pk_bf16_f32 v197, v46, v47
	ds_write_b64 v187, v[196:197] offset:1904
.Lcv_rm_0:
	s_or_b64 exec, exec, vcc
	s_and_saveexec_b64 vcc, s[34:35]
	s_cbranch_execz .Lcv_tr_0
	v_pk_mul_f32 v[16:17], v[16:17], v[206:207] op_sel_hi:[1,0]
	v_pk_mul_f32 v[18:19], v[18:19], v[206:207] op_sel_hi:[1,0]
	v_pk_mul_f32 v[20:21], v[20:21], v[206:207] op_sel:[0,1] op_sel_hi:[1,1]
	v_pk_mul_f32 v[22:23], v[22:23], v[206:207] op_sel:[0,1] op_sel_hi:[1,1]
	v_pk_mul_f32 v[24:25], v[24:25], v[208:209] op_sel_hi:[1,0]
	v_pk_mul_f32 v[26:27], v[26:27], v[208:209] op_sel_hi:[1,0]
	v_pk_mul_f32 v[28:29], v[28:29], v[208:209] op_sel:[0,1] op_sel_hi:[1,1]
	v_pk_mul_f32 v[30:31], v[30:31], v[208:209] op_sel:[0,1] op_sel_hi:[1,1]
	v_pk_mul_f32 v[32:33], v[32:33], v[210:211] op_sel_hi:[1,0]
	v_pk_mul_f32 v[34:35], v[34:35], v[210:211] op_sel_hi:[1,0]
	v_pk_mul_f32 v[36:37], v[36:37], v[210:211] op_sel:[0,1] op_sel_hi:[1,1]
	v_pk_mul_f32 v[38:39], v[38:39], v[210:211] op_sel:[0,1] op_sel_hi:[1,1]
	v_pk_mul_f32 v[40:41], v[40:41], v[212:213] op_sel_hi:[1,0]
	v_pk_mul_f32 v[42:43], v[42:43], v[212:213] op_sel_hi:[1,0]
	v_pk_mul_f32 v[44:45], v[44:45], v[212:213] op_sel:[0,1] op_sel_hi:[1,1]
	v_pk_mul_f32 v[46:47], v[46:47], v[212:213] op_sel:[0,1] op_sel_hi:[1,1]
	v_cvt_pk_bf16_f32 v236, v16, v20
	v_cvt_pk_bf16_f32 v237, v24, v28
	v_cvt_pk_bf16_f32 v238, v32, v36
	v_cvt_pk_bf16_f32 v239, v40, v44
	ds_write_b128 v178, v[236:239]
	v_cvt_pk_bf16_f32 v198, v17, v21
	v_cvt_pk_bf16_f32 v199, v25, v29
	v_cvt_pk_bf16_f32 v200, v33, v37
	v_cvt_pk_bf16_f32 v201, v41, v45
	ds_write_b128 v178, v[198:201] offset:272
	v_cvt_pk_bf16_f32 v236, v18, v22
	v_cvt_pk_bf16_f32 v237, v26, v30
	v_cvt_pk_bf16_f32 v238, v34, v38
	v_cvt_pk_bf16_f32 v239, v42, v46
	ds_write_b128 v178, v[236:239] offset:544
	v_cvt_pk_bf16_f32 v198, v19, v23
	v_cvt_pk_bf16_f32 v199, v27, v31
	v_cvt_pk_bf16_f32 v200, v35, v39
	v_cvt_pk_bf16_f32 v201, v43, v47
	ds_write_b128 v178, v[198:201] offset:816
.Lcv_tr_0:
	s_or_b64 exec, exec, vcc
	s_cmp_ge_u32 s98, 4
	s_cbranch_scc1 .Lconv_skip
	ds_read_b128 v[206:209], v218 offset:32
	ds_read_b128 v[210:213], v218 offset:48
	v_lshlrev_b32_e32 v194, 16, v138
	v_and_b32_e32 v195, 0xffff0000, v138
	v_lshlrev_b32_e32 v196, 16, v139
	v_and_b32_e32 v197, 0xffff0000, v139
	v_pk_fma_f32 v[16:17], v[48:49], v[194:195], v[64:65]
	v_pk_fma_f32 v[18:19], v[50:51], v[196:197], v[66:67]
	v_lshlrev_b32_e32 v198, 16, v136
	v_and_b32_e32 v199, 0xffff0000, v136
	v_lshlrev_b32_e32 v200, 16, v137
	v_and_b32_e32 v201, 0xffff0000, v137
	v_pk_fma_f32 v[20:21], v[48:49], v[198:199], v[64:65]
	v_pk_fma_f32 v[22:23], v[50:51], v[200:201], v[66:67]
	v_pk_fma_f32 v[16:17], v[52:53], v[198:199], v[16:17]
	v_pk_fma_f32 v[18:19], v[54:55], v[200:201], v[18:19]
	v_lshlrev_b32_e32 v194, 16, v134
	v_and_b32_e32 v195, 0xffff0000, v134
	v_lshlrev_b32_e32 v196, 16, v135
	v_and_b32_e32 v197, 0xffff0000, v135
	v_pk_fma_f32 v[24:25], v[48:49], v[194:195], v[64:65]
	v_pk_fma_f32 v[26:27], v[50:51], v[196:197], v[66:67]
	v_pk_fma_f32 v[20:21], v[52:53], v[194:195], v[20:21]
	v_pk_fma_f32 v[22:23], v[54:55], v[196:197], v[22:23]
	v_pk_fma_f32 v[16:17], v[56:57], v[194:195], v[16:17]
	v_pk_fma_f32 v[18:19], v[58:59], v[196:197], v[18:19]
	s_waitcnt vmcnt(29)
	v_lshlrev_b32_e32 v198, 16, v132
	v_and_b32_e32 v199, 0xffff0000, v132
	v_lshlrev_b32_e32 v200, 16, v133
	v_and_b32_e32 v201, 0xffff0000, v133
	v_pk_fma_f32 v[28:29], v[48:49], v[198:199], v[64:65]
	v_pk_fma_f32 v[30:31], v[50:51], v[200:201], v[66:67]
	v_pk_fma_f32 v[24:25], v[52:53], v[198:199], v[24:25]
	v_pk_fma_f32 v[26:27], v[54:55], v[200:201], v[26:27]
	v_pk_fma_f32 v[20:21], v[56:57], v[198:199], v[20:21]
	v_pk_fma_f32 v[22:23], v[58:59], v[200:201], v[22:23]
	v_pk_fma_f32 v[16:17], v[60:61], v[198:199], v[16:17]
	v_pk_fma_f32 v[18:19], v[62:63], v[200:201], v[18:19]
	s_waitcnt vmcnt(28)
	v_lshlrev_b32_e32 v194, 16, v130
	v_and_b32_e32 v195, 0xffff0000, v130
	v_lshlrev_b32_e32 v196, 16, v131
	v_and_b32_e32 v197, 0xffff0000, v131
	v_pk_fma_f32 v[32:33], v[48:49], v[194:195], v[64:65]
	v_pk_fma_f32 v[34:35], v[50:51], v[196:197], v[66:67]
	v_pk_fma_f32 v[28:29], v[52:53], v[194:195], v[28:29]
	v_pk_fma_f32 v[30:31], v[54:55], v[196:197], v[30:31]
	v_pk_fma_f32 v[24:25], v[56:57], v[194:195], v[24:25]
	v_pk_fma_f32 v[26:27], v[58:59], v[196:197], v[26:27]
	v_pk_fma_f32 v[20:21], v[60:61], v[194:195], v[20:21]
	v_pk_fma_f32 v[22:23], v[62:63], v[196:197], v[22:23]
	s_waitcnt vmcnt(27)
	v_lshlrev_b32_e32 v198, 16, v128
	v_and_b32_e32 v199, 0xffff0000, v128
	v_lshlrev_b32_e32 v200, 16, v129
	v_and_b32_e32 v201, 0xffff0000, v129
	v_pk_fma_f32 v[36:37], v[48:49], v[198:199], v[64:65]
	v_pk_fma_f32 v[38:39], v[50:51], v[200:201], v[66:67]
	v_pk_fma_f32 v[32:33], v[52:53], v[198:199], v[32:33]
	v_pk_fma_f32 v[34:35], v[54:55], v[200:201], v[34:35]
	v_pk_fma_f32 v[28:29], v[56:57], v[198:199], v[28:29]
	v_pk_fma_f32 v[30:31], v[58:59], v[200:201], v[30:31]
	v_pk_fma_f32 v[24:25], v[60:61], v[198:199], v[24:25]
	v_pk_fma_f32 v[26:27], v[62:63], v[200:201], v[26:27]
	s_waitcnt vmcnt(26)
; __device__ __forceinline__ float bflo(unsigned u) { return __uint_as_float(u << 16); }
; __device__ __forceinline__ float bfhi(unsigned u) { return __uint_as_float(u & 0xffff0000u); }
; __device__ __forceinline__ float siluf_(float v) { return v * __builtin_amdgcn_rcpf(1.0f + __expf(-v)); }
; __device__ __forceinline__ void ssd_item(const Params& p, LAS unsigned char* lds, int bl, int head, int dry) {
;     ...
;                 for (int j = 0; j < 8; ++j) { const int i = seg * 8 + j;
;                     const u32x2 x0 = raw[i], x1 = raw[i + 1], x2 = raw[i + 2], x3 = raw[i + 3];
;                     float v0 = cbv[0] + cw0[0] * bflo(x0.x) + cw1[0] * bflo(x1.x) + cw2[0] * bflo(x2.x) + cw3[0] * bflo(x3.x);
;                     float v1 = cbv[1] + cw0[1] * bfhi(x0.x) + cw1[1] * bfhi(x1.x) + cw2[1] * bfhi(x2.x) + cw3[1] * bfhi(x3.x);
;                     float v2 = cbv[2] + cw0[2] * bflo(x0.y) + cw1[2] * bflo(x1.y) + cw2[2] * bflo(x2.y) + cw3[2] * bflo(x3.y);
;                     float v3 = cbv[3] + cw0[3] * bfhi(x0.y) + cw1[3] * bfhi(x1.y) + cw2[3] * bfhi(x2.y) + cw3[3] * bfhi(x3.y);
;                     val[j][0] = siluf_(v0); val[j][1] = siluf_(v1); val[j][2] = siluf_(v2); val[j][3] = siluf_(v3); }
	v_lshlrev_b32_e32 v194, 16, v126
	v_and_b32_e32 v195, 0xffff0000, v126
	v_lshlrev_b32_e32 v196, 16, v127
	v_and_b32_e32 v197, 0xffff0000, v127
	v_pk_fma_f32 v[40:41], v[48:49], v[194:195], v[64:65]
	v_pk_fma_f32 v[42:43], v[50:51], v[196:197], v[66:67]
	v_pk_fma_f32 v[36:37], v[52:53], v[194:195], v[36:37]
	v_pk_fma_f32 v[38:39], v[54:55], v[196:197], v[38:39]
	v_pk_fma_f32 v[32:33], v[56:57], v[194:195], v[32:33]
	v_pk_fma_f32 v[34:35], v[58:59], v[196:197], v[34:35]
	v_pk_fma_f32 v[28:29], v[60:61], v[194:195], v[28:29]
	v_pk_fma_f32 v[30:31], v[62:63], v[196:197], v[30:31]
	s_waitcnt vmcnt(25)
	v_lshlrev_b32_e32 v198, 16, v124
	v_and_b32_e32 v199, 0xffff0000, v124
	v_lshlrev_b32_e32 v200, 16, v125
	v_and_b32_e32 v201, 0xffff0000, v125
	v_pk_fma_f32 v[44:45], v[48:49], v[198:199], v[64:65]
	v_pk_fma_f32 v[46:47], v[50:51], v[200:201], v[66:67]
	v_pk_fma_f32 v[40:41], v[52:53], v[198:199], v[40:41]
	v_pk_fma_f32 v[42:43], v[54:55], v[200:201], v[42:43]
	v_pk_fma_f32 v[36:37], v[56:57], v[198:199], v[36:37]
	v_pk_fma_f32 v[38:39], v[58:59], v[200:201], v[38:39]
	v_pk_fma_f32 v[32:33], v[60:61], v[198:199], v[32:33]
	v_pk_fma_f32 v[34:35], v[62:63], v[200:201], v[34:35]
	s_waitcnt vmcnt(24)
	v_lshlrev_b32_e32 v194, 16, v122
	v_and_b32_e32 v195, 0xffff0000, v122
	v_lshlrev_b32_e32 v196, 16, v123
	v_and_b32_e32 v197, 0xffff0000, v123
	v_pk_fma_f32 v[44:45], v[52:53], v[194:195], v[44:45]
	v_pk_fma_f32 v[46:47], v[54:55], v[196:197], v[46:47]
	v_pk_fma_f32 v[40:41], v[56:57], v[194:195], v[40:41]
	v_pk_fma_f32 v[42:43], v[58:59], v[196:197], v[42:43]
	v_pk_fma_f32 v[36:37], v[60:61], v[194:195], v[36:37]
	v_pk_fma_f32 v[38:39], v[62:63], v[196:197], v[38:39]
	s_waitcnt vmcnt(23)
	v_lshlrev_b32_e32 v198, 16, v120
	v_and_b32_e32 v199, 0xffff0000, v120
	v_lshlrev_b32_e32 v200, 16, v121
	v_and_b32_e32 v201, 0xffff0000, v121
	v_pk_fma_f32 v[44:45], v[56:57], v[198:199], v[44:45]
	v_pk_fma_f32 v[46:47], v[58:59], v[200:201], v[46:47]
	v_pk_fma_f32 v[40:41], v[60:61], v[198:199], v[40:41]
	v_pk_fma_f32 v[42:43], v[62:63], v[200:201], v[42:43]
	s_waitcnt vmcnt(22)
	v_lshlrev_b32_e32 v194, 16, v118
	v_and_b32_e32 v195, 0xffff0000, v118
	v_lshlrev_b32_e32 v196, 16, v119
	v_and_b32_e32 v197, 0xffff0000, v119
	v_pk_fma_f32 v[44:45], v[60:61], v[194:195], v[44:45]
	v_pk_fma_f32 v[46:47], v[62:63], v[196:197], v[46:47]
	v_pk_mul_f32 v[202:203], v[16:17], v[214:215]
	v_pk_mul_f32 v[204:205], v[18:19], v[214:215]
	v_exp_f32_e32 v202, v202
	v_exp_f32_e32 v203, v203
	v_exp_f32_e32 v204, v204
	v_exp_f32_e32 v205, v205
	v_pk_add_f32 v[202:203], v[202:203], v[216:217]
	v_pk_add_f32 v[204:205], v[204:205], v[216:217]
	v_rcp_f32_e32 v202, v202
	v_rcp_f32_e32 v203, v203
	v_rcp_f32_e32 v204, v204
	v_rcp_f32_e32 v205, v205
	v_pk_mul_f32 v[16:17], v[16:17], v[202:203]
	v_pk_mul_f32 v[18:19], v[18:19], v[204:205]
	v_pk_mul_f32 v[202:203], v[20:21], v[214:215]
	v_pk_mul_f32 v[204:205], v[22:23], v[214:215]
	v_exp_f32_e32 v202, v202
	v_exp_f32_e32 v203, v203
	v_exp_f32_e32 v204, v204
	v_exp_f32_e32 v205, v205
	v_pk_add_f32 v[202:203], v[202:203], v[216:217]
	v_pk_add_f32 v[204:205], v[204:205], v[216:217]
	v_rcp_f32_e32 v202, v202
	v_rcp_f32_e32 v203, v203
	v_rcp_f32_e32 v204, v204
	v_rcp_f32_e32 v205, v205
	v_pk_mul_f32 v[20:21], v[20:21], v[202:203]
	v_pk_mul_f32 v[22:23], v[22:23], v[204:205]
	v_pk_mul_f32 v[202:203], v[24:25], v[214:215]
	v_pk_mul_f32 v[204:205], v[26:27], v[214:215]
	v_exp_f32_e32 v202, v202
	v_exp_f32_e32 v203, v203
	v_exp_f32_e32 v204, v204
	v_exp_f32_e32 v205, v205
	v_pk_add_f32 v[202:203], v[202:203], v[216:217]
	v_pk_add_f32 v[204:205], v[204:205], v[216:217]
	v_rcp_f32_e32 v202, v202
	v_rcp_f32_e32 v203, v203
	v_rcp_f32_e32 v204, v204
	v_rcp_f32_e32 v205, v205
	v_pk_mul_f32 v[24:25], v[24:25], v[202:203]
	v_pk_mul_f32 v[26:27], v[26:27], v[204:205]
	v_pk_mul_f32 v[202:203], v[28:29], v[214:215]
	v_pk_mul_f32 v[204:205], v[30:31], v[214:215]
	v_exp_f32_e32 v202, v202
	v_exp_f32_e32 v203, v203
	v_exp_f32_e32 v204, v204
	v_exp_f32_e32 v205, v205
	v_pk_add_f32 v[202:203], v[202:203], v[216:217]
	v_pk_add_f32 v[204:205], v[204:205], v[216:217]
	v_rcp_f32_e32 v202, v202
	v_rcp_f32_e32 v203, v203
	v_rcp_f32_e32 v204, v204
	v_rcp_f32_e32 v205, v205
	v_pk_mul_f32 v[28:29], v[28:29], v[202:203]
	v_pk_mul_f32 v[30:31], v[30:31], v[204:205]
	v_pk_mul_f32 v[202:203], v[32:33], v[214:215]
	v_pk_mul_f32 v[204:205], v[34:35], v[214:215]
	v_exp_f32_e32 v202, v202
	v_exp_f32_e32 v203, v203
	v_exp_f32_e32 v204, v204
	v_exp_f32_e32 v205, v205
	v_pk_add_f32 v[202:203], v[202:203], v[216:217]
	v_pk_add_f32 v[204:205], v[204:205], v[216:217]
	v_rcp_f32_e32 v202, v202
	v_rcp_f32_e32 v203, v203
	v_rcp_f32_e32 v204, v204
	v_rcp_f32_e32 v205, v205
	v_pk_mul_f32 v[32:33], v[32:33], v[202:203]
	v_pk_mul_f32 v[34:35], v[34:35], v[204:205]
	v_pk_mul_f32 v[202:203], v[36:37], v[214:215]
	v_pk_mul_f32 v[204:205], v[38:39], v[214:215]
	v_exp_f32_e32 v202, v202
	v_exp_f32_e32 v203, v203
	v_exp_f32_e32 v204, v204
	v_exp_f32_e32 v205, v205
	v_pk_add_f32 v[202:203], v[202:203], v[216:217]
	v_pk_add_f32 v[204:205], v[204:205], v[216:217]
	v_rcp_f32_e32 v202, v202
	v_rcp_f32_e32 v203, v203
	v_rcp_f32_e32 v204, v204
	v_rcp_f32_e32 v205, v205
	v_pk_mul_f32 v[36:37], v[36:37], v[202:203]
	v_pk_mul_f32 v[38:39], v[38:39], v[204:205]
	v_pk_mul_f32 v[202:203], v[40:41], v[214:215]
	v_pk_mul_f32 v[204:205], v[42:43], v[214:215]
	v_exp_f32_e32 v202, v202
	v_exp_f32_e32 v203, v203
	v_exp_f32_e32 v204, v204
	v_exp_f32_e32 v205, v205
	v_pk_add_f32 v[202:203], v[202:203], v[216:217]
	v_pk_add_f32 v[204:205], v[204:205], v[216:217]
	v_rcp_f32_e32 v202, v202
	v_rcp_f32_e32 v203, v203
	v_rcp_f32_e32 v204, v204
	v_rcp_f32_e32 v205, v205
	v_pk_mul_f32 v[40:41], v[40:41], v[202:203]
	v_pk_mul_f32 v[42:43], v[42:43], v[204:205]
	v_pk_mul_f32 v[202:203], v[44:45], v[214:215]
	v_pk_mul_f32 v[204:205], v[46:47], v[214:215]
	v_exp_f32_e32 v202, v202
	v_exp_f32_e32 v203, v203
	v_exp_f32_e32 v204, v204
	v_exp_f32_e32 v205, v205
	v_pk_add_f32 v[202:203], v[202:203], v[216:217]
	v_pk_add_f32 v[204:205], v[204:205], v[216:217]
	v_rcp_f32_e32 v202, v202
	v_rcp_f32_e32 v203, v203
	v_rcp_f32_e32 v204, v204
	v_rcp_f32_e32 v205, v205
	v_pk_mul_f32 v[44:45], v[44:45], v[202:203]
	v_pk_mul_f32 v[46:47], v[46:47], v[204:205]
	s_waitcnt lgkmcnt(0)
	s_and_saveexec_b64 vcc, s[38:39]
	s_cbranch_execz .Lcv_rm_1
; __device__ __forceinline__ unsigned cvt_pk_bf16(float lo, float hi) { unsigned r; asm volatile("v_cvt_pk_bf16_f32 %0, %1, %2" : "=v"(r) : "v"(lo), "v"(hi)); return r; }
; #define LAS __attribute__((address_space(3)))
; __device__ __forceinline__ float bflo(unsigned u) { return __uint_as_float(u << 16); }
; __device__ __forceinline__ float bfhi(unsigned u) { return __uint_as_float(u & 0xffff0000u); }
; __device__ __forceinline__ void ssd_item(const Params& p, LAS unsigned char* lds, int bl, int head, int dry) {
;     ...
;                 for (int j = 0; j < 8; ++j) { const int i = seg * 8 + j;
;                     const u32x2 x0 = raw[i], x1 = raw[i + 1], x2 = raw[i + 2], x3 = raw[i + 3];
;                     float v0 = cbv[0] + cw0[0] * bflo(x0.x) + cw1[0] * bflo(x1.x) + cw2[0] * bflo(x2.x) + cw3[0] * bflo(x3.x);
;                     float v1 = cbv[1] + cw0[1] * bfhi(x0.x) + cw1[1] * bfhi(x1.x) + cw2[1] * bfhi(x2.x) + cw3[1] * bfhi(x3.x);
;                     float v2 = cbv[2] + cw0[2] * bflo(x0.y) + cw1[2] * bflo(x1.y) + cw2[2] * bflo(x2.y) + cw3[2] * bflo(x3.y);
;                     float v3 = cbv[3] + cw0[3] * bfhi(x0.y) + cw1[3] * bfhi(x1.y) + cw2[3] * bfhi(x2.y) + cw3[3] * bfhi(x3.y);
;                     val[j][0] = siluf_(v0); val[j][1] = siluf_(v1); val[j][2] = siluf_(v2); val[j][3] = siluf_(v3); }
;                 const int lb = rg * 32 + seg * 8;
;                 if (kind != 0) { LAS bf16_t* rm = (kind == 1 ? BMm : CM) + lb * SLD + n4;
; #pragma unroll
;                     for (int j = 0; j < 8; ++j) { u32x2 o; o.x = cvt_pk_bf16(val[j][0], val[j][1]); o.y = cvt_pk_bf16(val[j][2], val[j][3]); *(LAS u32x2*)(rm + j * SLD) = o; } }
;                 if (kind != 2) { LAS float* sc = (kind == 0 ? fdt : fwl) + lb; LAS bf16_t* tp = (kind == 0 ? XT : BT) + n4 * SLD + lb;
;                     float scl[8];
; #pragma unroll
;                     for (int j = 0; j < 8; ++j) scl[j] = sc[j];
; #pragma unroll
;                     for (int e = 0; e < 4; ++e) { u32x4 o; o.x = cvt_pk_bf16(val[0][e] * scl[0], val[1][e] * scl[1]); o.y = cvt_pk_bf16(val[2][e] * scl[2], val[3][e] * scl[3]);
;                         o.z = cvt_pk_bf16(val[4][e] * scl[4], val[5][e] * scl[5]); o.w = cvt_pk_bf16(val[6][e] * scl[6], val[7][e] * scl[7]); *(LAS u32x4*)(tp + e * SLD) = o; } }
	v_cvt_pk_bf16_f32 v194, v16, v17
	v_cvt_pk_bf16_f32 v195, v18, v19
	ds_write_b64 v187, v[194:195] offset:2176
	v_cvt_pk_bf16_f32 v196, v20, v21
	v_cvt_pk_bf16_f32 v197, v22, v23
	ds_write_b64 v187, v[196:197] offset:2448
	v_cvt_pk_bf16_f32 v194, v24, v25
	v_cvt_pk_bf16_f32 v195, v26, v27
	ds_write_b64 v187, v[194:195] offset:2720
	v_cvt_pk_bf16_f32 v196, v28, v29
	v_cvt_pk_bf16_f32 v197, v30, v31
	ds_write_b64 v187, v[196:197] offset:2992
	v_cvt_pk_bf16_f32 v194, v32, v33
	v_cvt_pk_bf16_f32 v195, v34, v35
	ds_write_b64 v187, v[194:195] offset:3264
	v_cvt_pk_bf16_f32 v196, v36, v37
	v_cvt_pk_bf16_f32 v197, v38, v39
	ds_write_b64 v187, v[196:197] offset:3536
	v_cvt_pk_bf16_f32 v194, v40, v41
	v_cvt_pk_bf16_f32 v195, v42, v43
	ds_write_b64 v187, v[194:195] offset:3808
	v_cvt_pk_bf16_f32 v196, v44, v45
	v_cvt_pk_bf16_f32 v197, v46, v47
	ds_write_b64 v187, v[196:197] offset:4080
.Lcv_rm_1:
	s_or_b64 exec, exec, vcc
	s_and_saveexec_b64 vcc, s[34:35]
	s_cbranch_execz .Lcv_tr_1
	v_pk_mul_f32 v[16:17], v[16:17], v[206:207] op_sel_hi:[1,0]
	v_pk_mul_f32 v[18:19], v[18:19], v[206:207] op_sel_hi:[1,0]
	v_pk_mul_f32 v[20:21], v[20:21], v[206:207] op_sel:[0,1] op_sel_hi:[1,1]
	v_pk_mul_f32 v[22:23], v[22:23], v[206:207] op_sel:[0,1] op_sel_hi:[1,1]
	v_pk_mul_f32 v[24:25], v[24:25], v[208:209] op_sel_hi:[1,0]
	v_pk_mul_f32 v[26:27], v[26:27], v[208:209] op_sel_hi:[1,0]
	v_pk_mul_f32 v[28:29], v[28:29], v[208:209] op_sel:[0,1] op_sel_hi:[1,1]
	v_pk_mul_f32 v[30:31], v[30:31], v[208:209] op_sel:[0,1] op_sel_hi:[1,1]
	v_pk_mul_f32 v[32:33], v[32:33], v[210:211] op_sel_hi:[1,0]
	v_pk_mul_f32 v[34:35], v[34:35], v[210:211] op_sel_hi:[1,0]
	v_pk_mul_f32 v[36:37], v[36:37], v[210:211] op_sel:[0,1] op_sel_hi:[1,1]
	v_pk_mul_f32 v[38:39], v[38:39], v[210:211] op_sel:[0,1] op_sel_hi:[1,1]
	v_pk_mul_f32 v[40:41], v[40:41], v[212:213] op_sel_hi:[1,0]
	v_pk_mul_f32 v[42:43], v[42:43], v[212:213] op_sel_hi:[1,0]
	v_pk_mul_f32 v[44:45], v[44:45], v[212:213] op_sel:[0,1] op_sel_hi:[1,1]
	v_pk_mul_f32 v[46:47], v[46:47], v[212:213] op_sel:[0,1] op_sel_hi:[1,1]
	v_cvt_pk_bf16_f32 v236, v16, v20
	v_cvt_pk_bf16_f32 v237, v24, v28
	v_cvt_pk_bf16_f32 v238, v32, v36
	v_cvt_pk_bf16_f32 v239, v40, v44
	ds_write_b128 v178, v[236:239] offset:16
	v_cvt_pk_bf16_f32 v198, v17, v21
	v_cvt_pk_bf16_f32 v199, v25, v29
	v_cvt_pk_bf16_f32 v200, v33, v37
	v_cvt_pk_bf16_f32 v201, v41, v45
	ds_write_b128 v178, v[198:201] offset:288
	v_cvt_pk_bf16_f32 v236, v18, v22
	v_cvt_pk_bf16_f32 v237, v26, v30
	v_cvt_pk_bf16_f32 v238, v34, v38
	v_cvt_pk_bf16_f32 v239, v42, v46
	ds_write_b128 v178, v[236:239] offset:560
	v_cvt_pk_bf16_f32 v198, v19, v23
	v_cvt_pk_bf16_f32 v199, v27, v31
	v_cvt_pk_bf16_f32 v200, v35, v39
	v_cvt_pk_bf16_f32 v201, v43, v47
	ds_write_b128 v178, v[198:201] offset:832
.Lcv_tr_1:
	s_or_b64 exec, exec, vcc
	ds_read_b128 v[206:209], v218 offset:64
	ds_read_b128 v[210:213], v218 offset:80
	v_lshlrev_b32_e32 v194, 16, v122
	v_and_b32_e32 v195, 0xffff0000, v122
	v_lshlrev_b32_e32 v196, 16, v123
	v_and_b32_e32 v197, 0xffff0000, v123
	v_pk_fma_f32 v[16:17], v[48:49], v[194:195], v[64:65]
	v_pk_fma_f32 v[18:19], v[50:51], v[196:197], v[66:67]
	v_lshlrev_b32_e32 v198, 16, v120
	v_and_b32_e32 v199, 0xffff0000, v120
	v_lshlrev_b32_e32 v200, 16, v121
	v_and_b32_e32 v201, 0xffff0000, v121
	v_pk_fma_f32 v[20:21], v[48:49], v[198:199], v[64:65]
	v_pk_fma_f32 v[22:23], v[50:51], v[200:201], v[66:67]
	v_pk_fma_f32 v[16:17], v[52:53], v[198:199], v[16:17]
	v_pk_fma_f32 v[18:19], v[54:55], v[200:201], v[18:19]
	v_lshlrev_b32_e32 v194, 16, v118
	v_and_b32_e32 v195, 0xffff0000, v118
	v_lshlrev_b32_e32 v196, 16, v119
	v_and_b32_e32 v197, 0xffff0000, v119
	v_pk_fma_f32 v[24:25], v[48:49], v[194:195], v[64:65]
	v_pk_fma_f32 v[26:27], v[50:51], v[196:197], v[66:67]
	v_pk_fma_f32 v[20:21], v[52:53], v[194:195], v[20:21]
	v_pk_fma_f32 v[22:23], v[54:55], v[196:197], v[22:23]
	v_pk_fma_f32 v[16:17], v[56:57], v[194:195], v[16:17]
	v_pk_fma_f32 v[18:19], v[58:59], v[196:197], v[18:19]
	s_waitcnt vmcnt(21)
	v_lshlrev_b32_e32 v198, 16, v116
	v_and_b32_e32 v199, 0xffff0000, v116
	v_lshlrev_b32_e32 v200, 16, v117
	v_and_b32_e32 v201, 0xffff0000, v117
	v_pk_fma_f32 v[28:29], v[48:49], v[198:199], v[64:65]
	v_pk_fma_f32 v[30:31], v[50:51], v[200:201], v[66:67]
	v_pk_fma_f32 v[24:25], v[52:53], v[198:199], v[24:25]
	v_pk_fma_f32 v[26:27], v[54:55], v[200:201], v[26:27]
	v_pk_fma_f32 v[20:21], v[56:57], v[198:199], v[20:21]
	v_pk_fma_f32 v[22:23], v[58:59], v[200:201], v[22:23]
	v_pk_fma_f32 v[16:17], v[60:61], v[198:199], v[16:17]
	v_pk_fma_f32 v[18:19], v[62:63], v[200:201], v[18:19]
	s_waitcnt vmcnt(20)
	v_lshlrev_b32_e32 v194, 16, v114
	v_and_b32_e32 v195, 0xffff0000, v114
	v_lshlrev_b32_e32 v196, 16, v115
	v_and_b32_e32 v197, 0xffff0000, v115
	v_pk_fma_f32 v[32:33], v[48:49], v[194:195], v[64:65]
	v_pk_fma_f32 v[34:35], v[50:51], v[196:197], v[66:67]
	v_pk_fma_f32 v[28:29], v[52:53], v[194:195], v[28:29]
	v_pk_fma_f32 v[30:31], v[54:55], v[196:197], v[30:31]
	v_pk_fma_f32 v[24:25], v[56:57], v[194:195], v[24:25]
	v_pk_fma_f32 v[26:27], v[58:59], v[196:197], v[26:27]
	v_pk_fma_f32 v[20:21], v[60:61], v[194:195], v[20:21]
	v_pk_fma_f32 v[22:23], v[62:63], v[196:197], v[22:23]
	s_waitcnt vmcnt(19)
	v_lshlrev_b32_e32 v198, 16, v112
	v_and_b32_e32 v199, 0xffff0000, v112
	v_lshlrev_b32_e32 v200, 16, v113
	v_and_b32_e32 v201, 0xffff0000, v113
	v_pk_fma_f32 v[36:37], v[48:49], v[198:199], v[64:65]
	v_pk_fma_f32 v[38:39], v[50:51], v[200:201], v[66:67]
	v_pk_fma_f32 v[32:33], v[52:53], v[198:199], v[32:33]
	v_pk_fma_f32 v[34:35], v[54:55], v[200:201], v[34:35]
	v_pk_fma_f32 v[28:29], v[56:57], v[198:199], v[28:29]
	v_pk_fma_f32 v[30:31], v[58:59], v[200:201], v[30:31]
	v_pk_fma_f32 v[24:25], v[60:61], v[198:199], v[24:25]
	v_pk_fma_f32 v[26:27], v[62:63], v[200:201], v[26:27]
	s_waitcnt vmcnt(18)
; __device__ __forceinline__ float bflo(unsigned u) { return __uint_as_float(u << 16); }
; __device__ __forceinline__ float bfhi(unsigned u) { return __uint_as_float(u & 0xffff0000u); }
; __device__ __forceinline__ float siluf_(float v) { return v * __builtin_amdgcn_rcpf(1.0f + __expf(-v)); }
; __device__ __forceinline__ void ssd_item(const Params& p, LAS unsigned char* lds, int bl, int head, int dry) {
;     ...
;                 for (int j = 0; j < 8; ++j) { const int i = seg * 8 + j;
;                     const u32x2 x0 = raw[i], x1 = raw[i + 1], x2 = raw[i + 2], x3 = raw[i + 3];
;                     float v0 = cbv[0] + cw0[0] * bflo(x0.x) + cw1[0] * bflo(x1.x) + cw2[0] * bflo(x2.x) + cw3[0] * bflo(x3.x);
;                     float v1 = cbv[1] + cw0[1] * bfhi(x0.x) + cw1[1] * bfhi(x1.x) + cw2[1] * bfhi(x2.x) + cw3[1] * bfhi(x3.x);
;                     float v2 = cbv[2] + cw0[2] * bflo(x0.y) + cw1[2] * bflo(x1.y) + cw2[2] * bflo(x2.y) + cw3[2] * bflo(x3.y);
;                     float v3 = cbv[3] + cw0[3] * bfhi(x0.y) + cw1[3] * bfhi(x1.y) + cw2[3] * bfhi(x2.y) + cw3[3] * bfhi(x3.y);
;                     val[j][0] = siluf_(v0); val[j][1] = siluf_(v1); val[j][2] = siluf_(v2); val[j][3] = siluf_(v3); }
	v_lshlrev_b32_e32 v194, 16, v110
	v_and_b32_e32 v195, 0xffff0000, v110
	v_lshlrev_b32_e32 v196, 16, v111
	v_and_b32_e32 v197, 0xffff0000, v111
	v_pk_fma_f32 v[40:41], v[48:49], v[194:195], v[64:65]
	v_pk_fma_f32 v[42:43], v[50:51], v[196:197], v[66:67]
	v_pk_fma_f32 v[36:37], v[52:53], v[194:195], v[36:37]
	v_pk_fma_f32 v[38:39], v[54:55], v[196:197], v[38:39]
	v_pk_fma_f32 v[32:33], v[56:57], v[194:195], v[32:33]
	v_pk_fma_f32 v[34:35], v[58:59], v[196:197], v[34:35]
	v_pk_fma_f32 v[28:29], v[60:61], v[194:195], v[28:29]
	v_pk_fma_f32 v[30:31], v[62:63], v[196:197], v[30:31]
	s_waitcnt vmcnt(17)
	v_lshlrev_b32_e32 v198, 16, v108
	v_and_b32_e32 v199, 0xffff0000, v108
	v_lshlrev_b32_e32 v200, 16, v109
	v_and_b32_e32 v201, 0xffff0000, v109
	v_pk_fma_f32 v[44:45], v[48:49], v[198:199], v[64:65]
	v_pk_fma_f32 v[46:47], v[50:51], v[200:201], v[66:67]
	v_pk_fma_f32 v[40:41], v[52:53], v[198:199], v[40:41]
	v_pk_fma_f32 v[42:43], v[54:55], v[200:201], v[42:43]
	v_pk_fma_f32 v[36:37], v[56:57], v[198:199], v[36:37]
	v_pk_fma_f32 v[38:39], v[58:59], v[200:201], v[38:39]
	v_pk_fma_f32 v[32:33], v[60:61], v[198:199], v[32:33]
	v_pk_fma_f32 v[34:35], v[62:63], v[200:201], v[34:35]
	s_waitcnt vmcnt(16)
	v_lshlrev_b32_e32 v194, 16, v106
	v_and_b32_e32 v195, 0xffff0000, v106
	v_lshlrev_b32_e32 v196, 16, v107
	v_and_b32_e32 v197, 0xffff0000, v107
	v_pk_fma_f32 v[44:45], v[52:53], v[194:195], v[44:45]
	v_pk_fma_f32 v[46:47], v[54:55], v[196:197], v[46:47]
	v_pk_fma_f32 v[40:41], v[56:57], v[194:195], v[40:41]
	v_pk_fma_f32 v[42:43], v[58:59], v[196:197], v[42:43]
	v_pk_fma_f32 v[36:37], v[60:61], v[194:195], v[36:37]
	v_pk_fma_f32 v[38:39], v[62:63], v[196:197], v[38:39]
	s_waitcnt vmcnt(15)
	v_lshlrev_b32_e32 v198, 16, v102
	v_and_b32_e32 v199, 0xffff0000, v102
	v_lshlrev_b32_e32 v200, 16, v103
	v_and_b32_e32 v201, 0xffff0000, v103
	v_pk_fma_f32 v[44:45], v[56:57], v[198:199], v[44:45]
	v_pk_fma_f32 v[46:47], v[58:59], v[200:201], v[46:47]
	v_pk_fma_f32 v[40:41], v[60:61], v[198:199], v[40:41]
	v_pk_fma_f32 v[42:43], v[62:63], v[200:201], v[42:43]
	s_waitcnt vmcnt(14)
	v_lshlrev_b32_e32 v194, 16, v100
	v_and_b32_e32 v195, 0xffff0000, v100
	v_lshlrev_b32_e32 v196, 16, v101
	v_and_b32_e32 v197, 0xffff0000, v101
	v_pk_fma_f32 v[44:45], v[60:61], v[194:195], v[44:45]
	v_pk_fma_f32 v[46:47], v[62:63], v[196:197], v[46:47]
	v_pk_mul_f32 v[202:203], v[16:17], v[214:215]
	v_pk_mul_f32 v[204:205], v[18:19], v[214:215]
	v_exp_f32_e32 v202, v202
	v_exp_f32_e32 v203, v203
	v_exp_f32_e32 v204, v204
	v_exp_f32_e32 v205, v205
	v_pk_add_f32 v[202:203], v[202:203], v[216:217]
	v_pk_add_f32 v[204:205], v[204:205], v[216:217]
	v_rcp_f32_e32 v202, v202
	v_rcp_f32_e32 v203, v203
	v_rcp_f32_e32 v204, v204
	v_rcp_f32_e32 v205, v205
	v_pk_mul_f32 v[16:17], v[16:17], v[202:203]
	v_pk_mul_f32 v[18:19], v[18:19], v[204:205]
	v_pk_mul_f32 v[202:203], v[20:21], v[214:215]
	v_pk_mul_f32 v[204:205], v[22:23], v[214:215]
	v_exp_f32_e32 v202, v202
	v_exp_f32_e32 v203, v203
	v_exp_f32_e32 v204, v204
	v_exp_f32_e32 v205, v205
	v_pk_add_f32 v[202:203], v[202:203], v[216:217]
	v_pk_add_f32 v[204:205], v[204:205], v[216:217]
	v_rcp_f32_e32 v202, v202
	v_rcp_f32_e32 v203, v203
	v_rcp_f32_e32 v204, v204
	v_rcp_f32_e32 v205, v205
	v_pk_mul_f32 v[20:21], v[20:21], v[202:203]
	v_pk_mul_f32 v[22:23], v[22:23], v[204:205]
	v_pk_mul_f32 v[202:203], v[24:25], v[214:215]
	v_pk_mul_f32 v[204:205], v[26:27], v[214:215]
	v_exp_f32_e32 v202, v202
	v_exp_f32_e32 v203, v203
	v_exp_f32_e32 v204, v204
	v_exp_f32_e32 v205, v205
	v_pk_add_f32 v[202:203], v[202:203], v[216:217]
	v_pk_add_f32 v[204:205], v[204:205], v[216:217]
	v_rcp_f32_e32 v202, v202
	v_rcp_f32_e32 v203, v203
	v_rcp_f32_e32 v204, v204
	v_rcp_f32_e32 v205, v205
	v_pk_mul_f32 v[24:25], v[24:25], v[202:203]
	v_pk_mul_f32 v[26:27], v[26:27], v[204:205]
	v_pk_mul_f32 v[202:203], v[28:29], v[214:215]
	v_pk_mul_f32 v[204:205], v[30:31], v[214:215]
	v_exp_f32_e32 v202, v202
	v_exp_f32_e32 v203, v203
	v_exp_f32_e32 v204, v204
	v_exp_f32_e32 v205, v205
	v_pk_add_f32 v[202:203], v[202:203], v[216:217]
	v_pk_add_f32 v[204:205], v[204:205], v[216:217]
	v_rcp_f32_e32 v202, v202
	v_rcp_f32_e32 v203, v203
	v_rcp_f32_e32 v204, v204
	v_rcp_f32_e32 v205, v205
	v_pk_mul_f32 v[28:29], v[28:29], v[202:203]
	v_pk_mul_f32 v[30:31], v[30:31], v[204:205]
	v_pk_mul_f32 v[202:203], v[32:33], v[214:215]
	v_pk_mul_f32 v[204:205], v[34:35], v[214:215]
	v_exp_f32_e32 v202, v202
	v_exp_f32_e32 v203, v203
	v_exp_f32_e32 v204, v204
	v_exp_f32_e32 v205, v205
	v_pk_add_f32 v[202:203], v[202:203], v[216:217]
	v_pk_add_f32 v[204:205], v[204:205], v[216:217]
	v_rcp_f32_e32 v202, v202
	v_rcp_f32_e32 v203, v203
	v_rcp_f32_e32 v204, v204
	v_rcp_f32_e32 v205, v205
	v_pk_mul_f32 v[32:33], v[32:33], v[202:203]
	v_pk_mul_f32 v[34:35], v[34:35], v[204:205]
	v_pk_mul_f32 v[202:203], v[36:37], v[214:215]
	v_pk_mul_f32 v[204:205], v[38:39], v[214:215]
	v_exp_f32_e32 v202, v202
	v_exp_f32_e32 v203, v203
	v_exp_f32_e32 v204, v204
	v_exp_f32_e32 v205, v205
	v_pk_add_f32 v[202:203], v[202:203], v[216:217]
	v_pk_add_f32 v[204:205], v[204:205], v[216:217]
	v_rcp_f32_e32 v202, v202
	v_rcp_f32_e32 v203, v203
	v_rcp_f32_e32 v204, v204
	v_rcp_f32_e32 v205, v205
	v_pk_mul_f32 v[36:37], v[36:37], v[202:203]
	v_pk_mul_f32 v[38:39], v[38:39], v[204:205]
	v_pk_mul_f32 v[202:203], v[40:41], v[214:215]
	v_pk_mul_f32 v[204:205], v[42:43], v[214:215]
	v_exp_f32_e32 v202, v202
	v_exp_f32_e32 v203, v203
	v_exp_f32_e32 v204, v204
	v_exp_f32_e32 v205, v205
	v_pk_add_f32 v[202:203], v[202:203], v[216:217]
	v_pk_add_f32 v[204:205], v[204:205], v[216:217]
	v_rcp_f32_e32 v202, v202
	v_rcp_f32_e32 v203, v203
	v_rcp_f32_e32 v204, v204
	v_rcp_f32_e32 v205, v205
	v_pk_mul_f32 v[40:41], v[40:41], v[202:203]
	v_pk_mul_f32 v[42:43], v[42:43], v[204:205]
	v_pk_mul_f32 v[202:203], v[44:45], v[214:215]
	v_pk_mul_f32 v[204:205], v[46:47], v[214:215]
	v_exp_f32_e32 v202, v202
	v_exp_f32_e32 v203, v203
	v_exp_f32_e32 v204, v204
	v_exp_f32_e32 v205, v205
	v_pk_add_f32 v[202:203], v[202:203], v[216:217]
	v_pk_add_f32 v[204:205], v[204:205], v[216:217]
	v_rcp_f32_e32 v202, v202
	v_rcp_f32_e32 v203, v203
	v_rcp_f32_e32 v204, v204
	v_rcp_f32_e32 v205, v205
	v_pk_mul_f32 v[44:45], v[44:45], v[202:203]
	v_pk_mul_f32 v[46:47], v[46:47], v[204:205]
	s_waitcnt lgkmcnt(0)
	s_and_saveexec_b64 vcc, s[38:39]
	s_cbranch_execz .Lcv_rm_2
; __device__ __forceinline__ unsigned cvt_pk_bf16(float lo, float hi) { unsigned r; asm volatile("v_cvt_pk_bf16_f32 %0, %1, %2" : "=v"(r) : "v"(lo), "v"(hi)); return r; }
; #define LAS __attribute__((address_space(3)))
; __device__ __forceinline__ float bflo(unsigned u) { return __uint_as_float(u << 16); }
; __device__ __forceinline__ float bfhi(unsigned u) { return __uint_as_float(u & 0xffff0000u); }
; __device__ __forceinline__ void ssd_item(const Params& p, LAS unsigned char* lds, int bl, int head, int dry) {
;     ...
;                 for (int j = 0; j < 8; ++j) { const int i = seg * 8 + j;
;                     const u32x2 x0 = raw[i], x1 = raw[i + 1], x2 = raw[i + 2], x3 = raw[i + 3];
;                     float v0 = cbv[0] + cw0[0] * bflo(x0.x) + cw1[0] * bflo(x1.x) + cw2[0] * bflo(x2.x) + cw3[0] * bflo(x3.x);
;                     float v1 = cbv[1] + cw0[1] * bfhi(x0.x) + cw1[1] * bfhi(x1.x) + cw2[1] * bfhi(x2.x) + cw3[1] * bfhi(x3.x);
;                     float v2 = cbv[2] + cw0[2] * bflo(x0.y) + cw1[2] * bflo(x1.y) + cw2[2] * bflo(x2.y) + cw3[2] * bflo(x3.y);
;                     float v3 = cbv[3] + cw0[3] * bfhi(x0.y) + cw1[3] * bfhi(x1.y) + cw2[3] * bfhi(x2.y) + cw3[3] * bfhi(x3.y);
;                     val[j][0] = siluf_(v0); val[j][1] = siluf_(v1); val[j][2] = siluf_(v2); val[j][3] = siluf_(v3); }
;                 const int lb = rg * 32 + seg * 8;
;                 if (kind != 0) { LAS bf16_t* rm = (kind == 1 ? BMm : CM) + lb * SLD + n4;
; #pragma unroll
;                     for (int j = 0; j < 8; ++j) { u32x2 o; o.x = cvt_pk_bf16(val[j][0], val[j][1]); o.y = cvt_pk_bf16(val[j][2], val[j][3]); *(LAS u32x2*)(rm + j * SLD) = o; } }
;                 if (kind != 2) { LAS float* sc = (kind == 0 ? fdt : fwl) + lb; LAS bf16_t* tp = (kind == 0 ? XT : BT) + n4 * SLD + lb;
;                     float scl[8];
; #pragma unroll
;                     for (int j = 0; j < 8; ++j) scl[j] = sc[j];
; #pragma unroll
;                     for (int e = 0; e < 4; ++e) { u32x4 o; o.x = cvt_pk_bf16(val[0][e] * scl[0], val[1][e] * scl[1]); o.y = cvt_pk_bf16(val[2][e] * scl[2], val[3][e] * scl[3]);
;                         o.z = cvt_pk_bf16(val[4][e] * scl[4], val[5][e] * scl[5]); o.w = cvt_pk_bf16(val[6][e] * scl[6], val[7][e] * scl[7]); *(LAS u32x4*)(tp + e * SLD) = o; } }
	v_cvt_pk_bf16_f32 v194, v16, v17
	v_cvt_pk_bf16_f32 v195, v18, v19
	ds_write_b64 v187, v[194:195] offset:4352
	v_cvt_pk_bf16_f32 v196, v20, v21
	v_cvt_pk_bf16_f32 v197, v22, v23
	ds_write_b64 v187, v[196:197] offset:4624
	v_cvt_pk_bf16_f32 v194, v24, v25
	v_cvt_pk_bf16_f32 v195, v26, v27
	ds_write_b64 v187, v[194:195] offset:4896
	v_cvt_pk_bf16_f32 v196, v28, v29
	v_cvt_pk_bf16_f32 v197, v30, v31
	ds_write_b64 v187, v[196:197] offset:5168
	v_cvt_pk_bf16_f32 v194, v32, v33
	v_cvt_pk_bf16_f32 v195, v34, v35
	ds_write_b64 v187, v[194:195] offset:5440
	v_cvt_pk_bf16_f32 v196, v36, v37
	v_cvt_pk_bf16_f32 v197, v38, v39
	ds_write_b64 v187, v[196:197] offset:5712
	v_cvt_pk_bf16_f32 v194, v40, v41
	v_cvt_pk_bf16_f32 v195, v42, v43
	ds_write_b64 v187, v[194:195] offset:5984
	v_cvt_pk_bf16_f32 v196, v44, v45
	v_cvt_pk_bf16_f32 v197, v46, v47
	ds_write_b64 v187, v[196:197] offset:6256
.Lcv_rm_2:
	s_or_b64 exec, exec, vcc
	s_and_saveexec_b64 vcc, s[34:35]
	s_cbranch_execz .Lcv_tr_2
	v_pk_mul_f32 v[16:17], v[16:17], v[206:207] op_sel_hi:[1,0]
	v_pk_mul_f32 v[18:19], v[18:19], v[206:207] op_sel_hi:[1,0]
	v_pk_mul_f32 v[20:21], v[20:21], v[206:207] op_sel:[0,1] op_sel_hi:[1,1]
	v_pk_mul_f32 v[22:23], v[22:23], v[206:207] op_sel:[0,1] op_sel_hi:[1,1]
	v_pk_mul_f32 v[24:25], v[24:25], v[208:209] op_sel_hi:[1,0]
	v_pk_mul_f32 v[26:27], v[26:27], v[208:209] op_sel_hi:[1,0]
	v_pk_mul_f32 v[28:29], v[28:29], v[208:209] op_sel:[0,1] op_sel_hi:[1,1]
	v_pk_mul_f32 v[30:31], v[30:31], v[208:209] op_sel:[0,1] op_sel_hi:[1,1]
	v_pk_mul_f32 v[32:33], v[32:33], v[210:211] op_sel_hi:[1,0]
	v_pk_mul_f32 v[34:35], v[34:35], v[210:211] op_sel_hi:[1,0]
	v_pk_mul_f32 v[36:37], v[36:37], v[210:211] op_sel:[0,1] op_sel_hi:[1,1]
	v_pk_mul_f32 v[38:39], v[38:39], v[210:211] op_sel:[0,1] op_sel_hi:[1,1]
	v_pk_mul_f32 v[40:41], v[40:41], v[212:213] op_sel_hi:[1,0]
	v_pk_mul_f32 v[42:43], v[42:43], v[212:213] op_sel_hi:[1,0]
	v_pk_mul_f32 v[44:45], v[44:45], v[212:213] op_sel:[0,1] op_sel_hi:[1,1]
	v_pk_mul_f32 v[46:47], v[46:47], v[212:213] op_sel:[0,1] op_sel_hi:[1,1]
	v_cvt_pk_bf16_f32 v236, v16, v20
	v_cvt_pk_bf16_f32 v237, v24, v28
	v_cvt_pk_bf16_f32 v238, v32, v36
	v_cvt_pk_bf16_f32 v239, v40, v44
	ds_write_b128 v178, v[236:239] offset:32
	v_cvt_pk_bf16_f32 v198, v17, v21
	v_cvt_pk_bf16_f32 v199, v25, v29
	v_cvt_pk_bf16_f32 v200, v33, v37
	v_cvt_pk_bf16_f32 v201, v41, v45
	ds_write_b128 v178, v[198:201] offset:304
	v_cvt_pk_bf16_f32 v236, v18, v22
	v_cvt_pk_bf16_f32 v237, v26, v30
	v_cvt_pk_bf16_f32 v238, v34, v38
	v_cvt_pk_bf16_f32 v239, v42, v46
	ds_write_b128 v178, v[236:239] offset:576
	v_cvt_pk_bf16_f32 v198, v19, v23
	v_cvt_pk_bf16_f32 v199, v27, v31
	v_cvt_pk_bf16_f32 v200, v35, v39
	v_cvt_pk_bf16_f32 v201, v43, v47
	ds_write_b128 v178, v[198:201] offset:848
.Lcv_tr_2:
	s_or_b64 exec, exec, vcc
	ds_read_b128 v[206:209], v218 offset:96
	ds_read_b128 v[210:213], v218 offset:112
	v_lshlrev_b32_e32 v194, 16, v106
	v_and_b32_e32 v195, 0xffff0000, v106
	v_lshlrev_b32_e32 v196, 16, v107
	v_and_b32_e32 v197, 0xffff0000, v107
	v_pk_fma_f32 v[16:17], v[48:49], v[194:195], v[64:65]
	v_pk_fma_f32 v[18:19], v[50:51], v[196:197], v[66:67]
	v_lshlrev_b32_e32 v198, 16, v102
	v_and_b32_e32 v199, 0xffff0000, v102
	v_lshlrev_b32_e32 v200, 16, v103
	v_and_b32_e32 v201, 0xffff0000, v103
	v_pk_fma_f32 v[20:21], v[48:49], v[198:199], v[64:65]
	v_pk_fma_f32 v[22:23], v[50:51], v[200:201], v[66:67]
	v_pk_fma_f32 v[16:17], v[52:53], v[198:199], v[16:17]
	v_pk_fma_f32 v[18:19], v[54:55], v[200:201], v[18:19]
	v_lshlrev_b32_e32 v194, 16, v100
	v_and_b32_e32 v195, 0xffff0000, v100
	v_lshlrev_b32_e32 v196, 16, v101
	v_and_b32_e32 v197, 0xffff0000, v101
	v_pk_fma_f32 v[24:25], v[48:49], v[194:195], v[64:65]
	v_pk_fma_f32 v[26:27], v[50:51], v[196:197], v[66:67]
	v_pk_fma_f32 v[20:21], v[52:53], v[194:195], v[20:21]
	v_pk_fma_f32 v[22:23], v[54:55], v[196:197], v[22:23]
	v_pk_fma_f32 v[16:17], v[56:57], v[194:195], v[16:17]
	v_pk_fma_f32 v[18:19], v[58:59], v[196:197], v[18:19]
	s_waitcnt vmcnt(13)
	v_lshlrev_b32_e32 v198, 16, v94
	v_and_b32_e32 v199, 0xffff0000, v94
	v_lshlrev_b32_e32 v200, 16, v95
	v_and_b32_e32 v201, 0xffff0000, v95
	v_pk_fma_f32 v[28:29], v[48:49], v[198:199], v[64:65]
	v_pk_fma_f32 v[30:31], v[50:51], v[200:201], v[66:67]
	v_pk_fma_f32 v[24:25], v[52:53], v[198:199], v[24:25]
	v_pk_fma_f32 v[26:27], v[54:55], v[200:201], v[26:27]
	v_pk_fma_f32 v[20:21], v[56:57], v[198:199], v[20:21]
	v_pk_fma_f32 v[22:23], v[58:59], v[200:201], v[22:23]
	v_pk_fma_f32 v[16:17], v[60:61], v[198:199], v[16:17]
	v_pk_fma_f32 v[18:19], v[62:63], v[200:201], v[18:19]
	s_waitcnt vmcnt(12)
	v_lshlrev_b32_e32 v194, 16, v92
	v_and_b32_e32 v195, 0xffff0000, v92
	v_lshlrev_b32_e32 v196, 16, v93
	v_and_b32_e32 v197, 0xffff0000, v93
	v_pk_fma_f32 v[32:33], v[48:49], v[194:195], v[64:65]
	v_pk_fma_f32 v[34:35], v[50:51], v[196:197], v[66:67]
	v_pk_fma_f32 v[28:29], v[52:53], v[194:195], v[28:29]
	v_pk_fma_f32 v[30:31], v[54:55], v[196:197], v[30:31]
	v_pk_fma_f32 v[24:25], v[56:57], v[194:195], v[24:25]
	v_pk_fma_f32 v[26:27], v[58:59], v[196:197], v[26:27]
	v_pk_fma_f32 v[20:21], v[60:61], v[194:195], v[20:21]
	v_pk_fma_f32 v[22:23], v[62:63], v[196:197], v[22:23]
	s_waitcnt vmcnt(11)
	v_lshlrev_b32_e32 v198, 16, v88
	v_and_b32_e32 v199, 0xffff0000, v88
	v_lshlrev_b32_e32 v200, 16, v89
	v_and_b32_e32 v201, 0xffff0000, v89
	v_pk_fma_f32 v[36:37], v[48:49], v[198:199], v[64:65]
	v_pk_fma_f32 v[38:39], v[50:51], v[200:201], v[66:67]
	v_pk_fma_f32 v[32:33], v[52:53], v[198:199], v[32:33]
	v_pk_fma_f32 v[34:35], v[54:55], v[200:201], v[34:35]
	v_pk_fma_f32 v[28:29], v[56:57], v[198:199], v[28:29]
	v_pk_fma_f32 v[30:31], v[58:59], v[200:201], v[30:31]
	v_pk_fma_f32 v[24:25], v[60:61], v[198:199], v[24:25]
	v_pk_fma_f32 v[26:27], v[62:63], v[200:201], v[26:27]
	s_waitcnt vmcnt(10)
; #define LAS __attribute__((address_space(3)))
; __device__ __forceinline__ float bflo(unsigned u) { return __uint_as_float(u << 16); }
; __device__ __forceinline__ float bfhi(unsigned u) { return __uint_as_float(u & 0xffff0000u); }
; __device__ __forceinline__ float siluf_(float v) { return v * __builtin_amdgcn_rcpf(1.0f + __expf(-v)); }
; __device__ __forceinline__ void ssd_item(const Params& p, LAS unsigned char* lds, int bl, int head, int dry) {
;     ...
;                 for (int j = 0; j < 8; ++j) { const int i = seg * 8 + j;
;                     const u32x2 x0 = raw[i], x1 = raw[i + 1], x2 = raw[i + 2], x3 = raw[i + 3];
;                     float v0 = cbv[0] + cw0[0] * bflo(x0.x) + cw1[0] * bflo(x1.x) + cw2[0] * bflo(x2.x) + cw3[0] * bflo(x3.x);
;                     float v1 = cbv[1] + cw0[1] * bfhi(x0.x) + cw1[1] * bfhi(x1.x) + cw2[1] * bfhi(x2.x) + cw3[1] * bfhi(x3.x);
;                     float v2 = cbv[2] + cw0[2] * bflo(x0.y) + cw1[2] * bflo(x1.y) + cw2[2] * bflo(x2.y) + cw3[2] * bflo(x3.y);
;                     float v3 = cbv[3] + cw0[3] * bfhi(x0.y) + cw1[3] * bfhi(x1.y) + cw2[3] * bfhi(x2.y) + cw3[3] * bfhi(x3.y);
;                     val[j][0] = siluf_(v0); val[j][1] = siluf_(v1); val[j][2] = siluf_(v2); val[j][3] = siluf_(v3); }
;                 const int lb = rg * 32 + seg * 8;
;                 if (kind != 0) { LAS bf16_t* rm = (kind == 1 ? BMm : CM) + lb * SLD + n4;
	v_lshlrev_b32_e32 v194, 16, v86
	v_and_b32_e32 v195, 0xffff0000, v86
	v_lshlrev_b32_e32 v196, 16, v87
	v_and_b32_e32 v197, 0xffff0000, v87
	v_pk_fma_f32 v[40:41], v[48:49], v[194:195], v[64:65]
	v_pk_fma_f32 v[42:43], v[50:51], v[196:197], v[66:67]
	v_pk_fma_f32 v[36:37], v[52:53], v[194:195], v[36:37]
	v_pk_fma_f32 v[38:39], v[54:55], v[196:197], v[38:39]
	v_pk_fma_f32 v[32:33], v[56:57], v[194:195], v[32:33]
	v_pk_fma_f32 v[34:35], v[58:59], v[196:197], v[34:35]
	v_pk_fma_f32 v[28:29], v[60:61], v[194:195], v[28:29]
	v_pk_fma_f32 v[30:31], v[62:63], v[196:197], v[30:31]
	s_waitcnt vmcnt(9)
	v_lshlrev_b32_e32 v198, 16, v84
	v_and_b32_e32 v199, 0xffff0000, v84
	v_lshlrev_b32_e32 v200, 16, v85
	v_and_b32_e32 v201, 0xffff0000, v85
	v_pk_fma_f32 v[44:45], v[48:49], v[198:199], v[64:65]
	v_pk_fma_f32 v[46:47], v[50:51], v[200:201], v[66:67]
	v_pk_fma_f32 v[40:41], v[52:53], v[198:199], v[40:41]
	v_pk_fma_f32 v[42:43], v[54:55], v[200:201], v[42:43]
	v_pk_fma_f32 v[36:37], v[56:57], v[198:199], v[36:37]
	v_pk_fma_f32 v[38:39], v[58:59], v[200:201], v[38:39]
	v_pk_fma_f32 v[32:33], v[60:61], v[198:199], v[32:33]
	v_pk_fma_f32 v[34:35], v[62:63], v[200:201], v[34:35]
	s_waitcnt vmcnt(8)
	v_lshlrev_b32_e32 v194, 16, v82
	v_and_b32_e32 v195, 0xffff0000, v82
	v_lshlrev_b32_e32 v196, 16, v83
	v_and_b32_e32 v197, 0xffff0000, v83
	v_pk_fma_f32 v[44:45], v[52:53], v[194:195], v[44:45]
	v_pk_fma_f32 v[46:47], v[54:55], v[196:197], v[46:47]
	v_pk_fma_f32 v[40:41], v[56:57], v[194:195], v[40:41]
	v_pk_fma_f32 v[42:43], v[58:59], v[196:197], v[42:43]
	v_pk_fma_f32 v[36:37], v[60:61], v[194:195], v[36:37]
	v_pk_fma_f32 v[38:39], v[62:63], v[196:197], v[38:39]
	s_waitcnt vmcnt(7)
	v_lshlrev_b32_e32 v198, 16, v80
	v_and_b32_e32 v199, 0xffff0000, v80
	v_lshlrev_b32_e32 v200, 16, v81
	v_and_b32_e32 v201, 0xffff0000, v81
	v_pk_fma_f32 v[44:45], v[56:57], v[198:199], v[44:45]
	v_pk_fma_f32 v[46:47], v[58:59], v[200:201], v[46:47]
	v_pk_fma_f32 v[40:41], v[60:61], v[198:199], v[40:41]
	v_pk_fma_f32 v[42:43], v[62:63], v[200:201], v[42:43]
	s_waitcnt vmcnt(6)
	v_lshlrev_b32_e32 v194, 16, v78
	v_and_b32_e32 v195, 0xffff0000, v78
	v_lshlrev_b32_e32 v196, 16, v79
	v_and_b32_e32 v197, 0xffff0000, v79
	v_pk_fma_f32 v[44:45], v[60:61], v[194:195], v[44:45]
	v_pk_fma_f32 v[46:47], v[62:63], v[196:197], v[46:47]
	v_pk_mul_f32 v[202:203], v[16:17], v[214:215]
	v_pk_mul_f32 v[204:205], v[18:19], v[214:215]
	v_exp_f32_e32 v202, v202
	v_exp_f32_e32 v203, v203
	v_exp_f32_e32 v204, v204
	v_exp_f32_e32 v205, v205
	v_pk_add_f32 v[202:203], v[202:203], v[216:217]
	v_pk_add_f32 v[204:205], v[204:205], v[216:217]
	v_rcp_f32_e32 v202, v202
	v_rcp_f32_e32 v203, v203
	v_rcp_f32_e32 v204, v204
	v_rcp_f32_e32 v205, v205
	v_pk_mul_f32 v[16:17], v[16:17], v[202:203]
	v_pk_mul_f32 v[18:19], v[18:19], v[204:205]
	v_pk_mul_f32 v[202:203], v[20:21], v[214:215]
	v_pk_mul_f32 v[204:205], v[22:23], v[214:215]
	v_exp_f32_e32 v202, v202
	v_exp_f32_e32 v203, v203
	v_exp_f32_e32 v204, v204
	v_exp_f32_e32 v205, v205
	v_pk_add_f32 v[202:203], v[202:203], v[216:217]
	v_pk_add_f32 v[204:205], v[204:205], v[216:217]
	v_rcp_f32_e32 v202, v202
	v_rcp_f32_e32 v203, v203
	v_rcp_f32_e32 v204, v204
	v_rcp_f32_e32 v205, v205
	v_pk_mul_f32 v[20:21], v[20:21], v[202:203]
	v_pk_mul_f32 v[22:23], v[22:23], v[204:205]
	v_pk_mul_f32 v[202:203], v[24:25], v[214:215]
	v_pk_mul_f32 v[204:205], v[26:27], v[214:215]
	v_exp_f32_e32 v202, v202
	v_exp_f32_e32 v203, v203
	v_exp_f32_e32 v204, v204
	v_exp_f32_e32 v205, v205
	v_pk_add_f32 v[202:203], v[202:203], v[216:217]
	v_pk_add_f32 v[204:205], v[204:205], v[216:217]
	v_rcp_f32_e32 v202, v202
	v_rcp_f32_e32 v203, v203
	v_rcp_f32_e32 v204, v204
	v_rcp_f32_e32 v205, v205
	v_pk_mul_f32 v[24:25], v[24:25], v[202:203]
	v_pk_mul_f32 v[26:27], v[26:27], v[204:205]
	v_pk_mul_f32 v[202:203], v[28:29], v[214:215]
	v_pk_mul_f32 v[204:205], v[30:31], v[214:215]
	v_exp_f32_e32 v202, v202
	v_exp_f32_e32 v203, v203
	v_exp_f32_e32 v204, v204
	v_exp_f32_e32 v205, v205
	v_pk_add_f32 v[202:203], v[202:203], v[216:217]
	v_pk_add_f32 v[204:205], v[204:205], v[216:217]
	v_rcp_f32_e32 v202, v202
	v_rcp_f32_e32 v203, v203
	v_rcp_f32_e32 v204, v204
	v_rcp_f32_e32 v205, v205
	v_pk_mul_f32 v[28:29], v[28:29], v[202:203]
	v_pk_mul_f32 v[30:31], v[30:31], v[204:205]
	v_pk_mul_f32 v[202:203], v[32:33], v[214:215]
	v_pk_mul_f32 v[204:205], v[34:35], v[214:215]
	v_exp_f32_e32 v202, v202
	v_exp_f32_e32 v203, v203
	v_exp_f32_e32 v204, v204
	v_exp_f32_e32 v205, v205
	v_pk_add_f32 v[202:203], v[202:203], v[216:217]
	v_pk_add_f32 v[204:205], v[204:205], v[216:217]
	v_rcp_f32_e32 v202, v202
	v_rcp_f32_e32 v203, v203
	v_rcp_f32_e32 v204, v204
	v_rcp_f32_e32 v205, v205
	v_pk_mul_f32 v[32:33], v[32:33], v[202:203]
	v_pk_mul_f32 v[34:35], v[34:35], v[204:205]
	v_pk_mul_f32 v[202:203], v[36:37], v[214:215]
	v_pk_mul_f32 v[204:205], v[38:39], v[214:215]
	v_exp_f32_e32 v202, v202
	v_exp_f32_e32 v203, v203
	v_exp_f32_e32 v204, v204
	v_exp_f32_e32 v205, v205
	v_pk_add_f32 v[202:203], v[202:203], v[216:217]
	v_pk_add_f32 v[204:205], v[204:205], v[216:217]
	v_rcp_f32_e32 v202, v202
	v_rcp_f32_e32 v203, v203
	v_rcp_f32_e32 v204, v204
	v_rcp_f32_e32 v205, v205
	v_pk_mul_f32 v[36:37], v[36:37], v[202:203]
	v_pk_mul_f32 v[38:39], v[38:39], v[204:205]
	v_pk_mul_f32 v[202:203], v[40:41], v[214:215]
	v_pk_mul_f32 v[204:205], v[42:43], v[214:215]
	v_exp_f32_e32 v202, v202
	v_exp_f32_e32 v203, v203
	v_exp_f32_e32 v204, v204
	v_exp_f32_e32 v205, v205
	v_pk_add_f32 v[202:203], v[202:203], v[216:217]
	v_pk_add_f32 v[204:205], v[204:205], v[216:217]
	v_rcp_f32_e32 v202, v202
	v_rcp_f32_e32 v203, v203
	v_rcp_f32_e32 v204, v204
	v_rcp_f32_e32 v205, v205
	v_pk_mul_f32 v[40:41], v[40:41], v[202:203]
	v_pk_mul_f32 v[42:43], v[42:43], v[204:205]
	v_pk_mul_f32 v[202:203], v[44:45], v[214:215]
	v_pk_mul_f32 v[204:205], v[46:47], v[214:215]
	v_exp_f32_e32 v202, v202
	v_exp_f32_e32 v203, v203
	v_exp_f32_e32 v204, v204
	v_exp_f32_e32 v205, v205
	v_pk_add_f32 v[202:203], v[202:203], v[216:217]
	v_pk_add_f32 v[204:205], v[204:205], v[216:217]
	v_rcp_f32_e32 v202, v202
	v_rcp_f32_e32 v203, v203
	v_rcp_f32_e32 v204, v204
	v_rcp_f32_e32 v205, v205
	v_pk_mul_f32 v[44:45], v[44:45], v[202:203]
	v_pk_mul_f32 v[46:47], v[46:47], v[204:205]
	s_waitcnt lgkmcnt(0)
	s_and_saveexec_b64 vcc, s[38:39]
	s_cbranch_execz .Lcv_rm_3
; __device__ __forceinline__ unsigned cvt_pk_bf16(float lo, float hi) { unsigned r; asm volatile("v_cvt_pk_bf16_f32 %0, %1, %2" : "=v"(r) : "v"(lo), "v"(hi)); return r; }
; #define LAS __attribute__((address_space(3)))
; __device__ __forceinline__ void ssd_item(const Params& p, LAS unsigned char* lds, int bl, int head, int dry) {
;     ...
;                 if (kind != 0) { LAS bf16_t* rm = (kind == 1 ? BMm : CM) + lb * SLD + n4;
; #pragma unroll
;                     for (int j = 0; j < 8; ++j) { u32x2 o; o.x = cvt_pk_bf16(val[j][0], val[j][1]); o.y = cvt_pk_bf16(val[j][2], val[j][3]); *(LAS u32x2*)(rm + j * SLD) = o; } }
;                 if (kind != 2) { LAS float* sc = (kind == 0 ? fdt : fwl) + lb; LAS bf16_t* tp = (kind == 0 ? XT : BT) + n4 * SLD + lb;
;                     float scl[8];
; #pragma unroll
;                     for (int j = 0; j < 8; ++j) scl[j] = sc[j];
; #pragma unroll
;                     for (int e = 0; e < 4; ++e) { u32x4 o; o.x = cvt_pk_bf16(val[0][e] * scl[0], val[1][e] * scl[1]); o.y = cvt_pk_bf16(val[2][e] * scl[2], val[3][e] * scl[3]);
;                         o.z = cvt_pk_bf16(val[4][e] * scl[4], val[5][e] * scl[5]); o.w = cvt_pk_bf16(val[6][e] * scl[6], val[7][e] * scl[7]); *(LAS u32x4*)(tp + e * SLD) = o; } }
	v_cvt_pk_bf16_f32 v194, v16, v17
	v_cvt_pk_bf16_f32 v195, v18, v19
	ds_write_b64 v187, v[194:195] offset:6528
	v_cvt_pk_bf16_f32 v196, v20, v21
	v_cvt_pk_bf16_f32 v197, v22, v23
	ds_write_b64 v187, v[196:197] offset:6800
	v_cvt_pk_bf16_f32 v194, v24, v25
	v_cvt_pk_bf16_f32 v195, v26, v27
	ds_write_b64 v187, v[194:195] offset:7072
	v_cvt_pk_bf16_f32 v196, v28, v29
	v_cvt_pk_bf16_f32 v197, v30, v31
	ds_write_b64 v187, v[196:197] offset:7344
	v_cvt_pk_bf16_f32 v194, v32, v33
	v_cvt_pk_bf16_f32 v195, v34, v35
	ds_write_b64 v187, v[194:195] offset:7616
	v_cvt_pk_bf16_f32 v196, v36, v37
	v_cvt_pk_bf16_f32 v197, v38, v39
	ds_write_b64 v187, v[196:197] offset:7888
	v_cvt_pk_bf16_f32 v194, v40, v41
	v_cvt_pk_bf16_f32 v195, v42, v43
	ds_write_b64 v187, v[194:195] offset:8160
	v_cvt_pk_bf16_f32 v196, v44, v45
	v_cvt_pk_bf16_f32 v197, v46, v47
	ds_write_b64 v187, v[196:197] offset:8432
.Lcv_rm_3:
	s_or_b64 exec, exec, vcc
	s_and_saveexec_b64 vcc, s[34:35]
	s_cbranch_execz .Lcv_tr_3
	v_pk_mul_f32 v[16:17], v[16:17], v[206:207] op_sel_hi:[1,0]
	v_pk_mul_f32 v[18:19], v[18:19], v[206:207] op_sel_hi:[1,0]
	v_pk_mul_f32 v[20:21], v[20:21], v[206:207] op_sel:[0,1] op_sel_hi:[1,1]
	v_pk_mul_f32 v[22:23], v[22:23], v[206:207] op_sel:[0,1] op_sel_hi:[1,1]
	v_pk_mul_f32 v[24:25], v[24:25], v[208:209] op_sel_hi:[1,0]
	v_pk_mul_f32 v[26:27], v[26:27], v[208:209] op_sel_hi:[1,0]
	v_pk_mul_f32 v[28:29], v[28:29], v[208:209] op_sel:[0,1] op_sel_hi:[1,1]
	v_pk_mul_f32 v[30:31], v[30:31], v[208:209] op_sel:[0,1] op_sel_hi:[1,1]
	v_pk_mul_f32 v[32:33], v[32:33], v[210:211] op_sel_hi:[1,0]
	v_pk_mul_f32 v[34:35], v[34:35], v[210:211] op_sel_hi:[1,0]
	v_pk_mul_f32 v[36:37], v[36:37], v[210:211] op_sel:[0,1] op_sel_hi:[1,1]
	v_pk_mul_f32 v[38:39], v[38:39], v[210:211] op_sel:[0,1] op_sel_hi:[1,1]
	v_pk_mul_f32 v[40:41], v[40:41], v[212:213] op_sel_hi:[1,0]
	v_pk_mul_f32 v[42:43], v[42:43], v[212:213] op_sel_hi:[1,0]
	v_pk_mul_f32 v[44:45], v[44:45], v[212:213] op_sel:[0,1] op_sel_hi:[1,1]
	v_pk_mul_f32 v[46:47], v[46:47], v[212:213] op_sel:[0,1] op_sel_hi:[1,1]
	v_cvt_pk_bf16_f32 v236, v16, v20
	v_cvt_pk_bf16_f32 v237, v24, v28
	v_cvt_pk_bf16_f32 v238, v32, v36
	v_cvt_pk_bf16_f32 v239, v40, v44
	ds_write_b128 v178, v[236:239] offset:48
	v_cvt_pk_bf16_f32 v198, v17, v21
	v_cvt_pk_bf16_f32 v199, v25, v29
	v_cvt_pk_bf16_f32 v200, v33, v37
	v_cvt_pk_bf16_f32 v201, v41, v45
	ds_write_b128 v178, v[198:201] offset:320
	v_cvt_pk_bf16_f32 v236, v18, v22
	v_cvt_pk_bf16_f32 v237, v26, v30
	v_cvt_pk_bf16_f32 v238, v34, v38
	v_cvt_pk_bf16_f32 v239, v42, v46
	ds_write_b128 v178, v[236:239] offset:592
	v_cvt_pk_bf16_f32 v198, v19, v23
	v_cvt_pk_bf16_f32 v199, v27, v31
	v_cvt_pk_bf16_f32 v200, v35, v39
	v_cvt_pk_bf16_f32 v201, v43, v47
	ds_write_b128 v178, v[198:201] offset:864
